# V^T chunk scratch also in 16-byte-unit layout (prep stores, state MFMA loads and mLSTM-output loads coalesced)
# speedup vs baseline: 1.2322x; 1.0189x over previous
.LBB0_407:
	s_cmp_lg_u32 s4, 0x18000
	s_cselect_b32 s36, s4, 0x12000
	v_lshl_add_u64 v[138:139], s[36:37], 1, v[72:73]
	v_add_co_u32_e32 v140, vcc, s92, v138
	s_nop 1
	v_addc_co_u32_e32 v141, vcc, 0, v139, vcc
	v_add_co_u32_e32 v142, vcc, s91, v138
	s_nop 1
	v_addc_co_u32_e32 v143, vcc, 0, v139, vcc
	s_add_i32 vcc_lo, s36, 0x2400
	s_mov_b32 vcc_hi, s37
	v_lshl_add_u64 v[144:145], vcc, 1, v[72:73]
	s_add_i32 vcc_lo, s36, 0x3000
	v_lshl_add_u64 v[146:147], vcc, 1, v[72:73]
	s_add_i32 vcc_lo, s36, 0x3c00
	v_lshl_add_u64 v[150:151], vcc, 1, v[72:73]
	s_add_i32 vcc_lo, s36, 0x4800
	v_lshl_add_u64 v[152:153], vcc, 1, v[72:73]
	s_addk_i32 s36, 0x5400
	global_load_dwordx2 v[138:139], v[138:139], off
	s_nop 0
	global_load_dwordx2 v[140:141], v[140:141], off offset:2048
	s_nop 0
	global_load_dwordx2 v[142:143], v[142:143], off
	s_nop 0
	global_load_dwordx2 v[144:145], v[144:145], off
	v_lshl_add_u64 v[174:175], s[36:37], 1, v[72:73]
	global_load_dwordx2 v[148:149], v[146:147], off
	s_nop 0
	global_load_dwordx2 v[150:151], v[150:151], off
	s_nop 0
	global_load_dwordx2 v[152:153], v[152:153], off
	s_nop 0
	global_load_dwordx2 v[146:147], v[174:175], off
	v_pk_mul_f32 v[174:175], v[98:99], v[164:165]
	v_pk_mul_f32 v[178:179], v[102:103], v[162:163]
	v_pk_mul_f32 v[184:185], v[80:81], v[168:169]
	v_pk_mul_f32 v[188:189], v[78:79], v[166:167]
	v_mov_b32_e32 v190, v174
	v_mov_b32_e32 v191, v178
	v_mov_b32_e32 v178, v175
	v_mov_b32_e32 v174, v184
	v_mov_b32_e32 v175, v188
	v_mov_b32_e32 v158, v165
	s_waitcnt vmcnt(15)
	v_lshlrev_b32_e32 v165, 16, v170
	v_mov_b32_e32 v160, v163
	v_and_b32_e32 v163, 0xffff0000, v170
	v_pk_add_f32 v[190:191], v[64:65], v[190:191]
	v_pk_add_f32 v[174:175], v[66:67], v[174:175]
	v_mov_b32_e32 v188, v185
	v_pk_mul_f32 v[184:185], v[98:99], v[158:159]
	v_mov_b32_e32 v158, v165
	v_pk_mul_f32 v[194:195], v[102:103], v[160:161]
	v_mov_b32_e32 v160, v163
	v_pk_add_f32 v[190:191], v[190:191], v[178:179]
	v_pk_add_f32 v[178:179], v[174:175], v[188:189]
	v_pk_mul_f32 v[188:189], v[108:109], v[158:159]
	v_pk_mul_f32 v[196:197], v[112:113], v[160:161]
	v_mov_b32_e32 v198, v189
	v_mov_b32_e32 v199, v197
	v_pk_add_f32 v[190:191], v[190:191], v[198:199]
	v_mov_b32_e32 v189, v196
	v_pk_add_f32 v[188:189], v[188:189], v[190:191]
	s_waitcnt vmcnt(14)
	v_lshlrev_b32_e32 v164, 16, v172
	v_mul_f32_e32 v154, 0xbfb8aa3b, v188
	v_exp_f32_e32 v154, v154
	v_and_b32_e32 v162, 0xffff0000, v172
	v_mov_b32_e32 v198, v184
	v_mov_b32_e32 v199, v194
	v_add_f32_e32 v154, 1.0, v154
	v_rcp_f32_e32 v190, v154
	v_mul_f32_e32 v154, 0xbfb8aa3b, v189
	v_exp_f32_e32 v154, v154
	v_pk_mul_f32 v[192:193], v[108:109], v[164:165]
	v_pk_add_f32 v[198:199], v[64:65], v[198:199]
	v_mov_b32_e32 v194, v185
	v_add_f32_e32 v154, 1.0, v154
	v_rcp_f32_e32 v191, v154
	v_pk_add_f32 v[184:185], v[198:199], v[194:195]
	v_mov_b32_e32 v194, v193
	v_mov_b32_e32 v156, v167
	v_pk_mul_f32 v[196:197], v[188:189], v[190:191]
	v_and_b32_e32 v199, 0xffff0000, v171
	v_pk_mul_f32 v[188:189], v[90:91], v[196:197]
	v_cvt_pk_bf16_f32 v166, v196, v197
	v_add_f32_e32 v154, 0, v188
	v_add_f32_e32 v202, v154, v189
	v_pk_mul_f32 v[188:189], v[92:93], v[196:197]
	v_pk_mul_f32 v[200:201], v[78:79], v[156:157]
	v_add_f32_e32 v154, 0, v188
	v_add_f32_e32 v203, v154, v189
	v_pk_fma_f32 v[188:189], v[24:25], v[196:197], 0 op_sel_hi:[1,0,0]
	v_mov_b32_e32 v156, v199
	v_pk_fma_f32 v[190:191], v[44:45], v[196:197], v[188:189] op_sel:[0,1,0]
	v_pk_mul_f32 v[188:189], v[82:83], v[196:197]
	v_lshlrev_b32_e32 v168, 16, v173
	v_add_f32_e32 v154, 0, v188
	v_add_f32_e32 v204, v154, v189
	v_pk_mul_f32 v[188:189], v[84:85], v[196:197]
	v_and_b32_e32 v198, 0xffff0000, v173
	v_add_f32_e32 v154, 0, v188
	v_add_f32_e32 v208, v154, v189
	v_pk_fma_f32 v[188:189], v[26:27], v[196:197], 0 op_sel_hi:[1,0,0]
	v_lshl_add_u64 v[174:175], s[58:59], 0, v[132:133]
	v_pk_fma_f32 v[188:189], v[46:47], v[196:197], v[188:189] op_sel:[0,1,0]
	v_pk_mul_f32 v[196:197], v[112:113], v[162:163]
	v_pk_mul_f32 v[158:159], v[100:101], v[158:159]
	v_mov_b32_e32 v195, v197
	v_pk_add_f32 v[184:185], v[194:195], v[184:185]
	v_mov_b32_e32 v193, v196
	v_pk_add_f32 v[184:185], v[192:193], v[184:185]
	v_pk_mul_f32 v[160:161], v[104:105], v[160:161]
	v_mul_f32_e32 v154, 0xbfb8aa3b, v184
	v_exp_f32_e32 v154, v154
	v_pk_mul_f32 v[210:211], v[104:105], v[162:163]
	s_waitcnt vmcnt(13)
	v_and_b32_e32 v220, 0xffff0000, v181
	s_waitcnt vmcnt(12)
	v_and_b32_e32 v221, 0xffff0000, v183
	v_add_f32_e32 v154, 1.0, v154
	v_rcp_f32_e32 v192, v154
	v_mul_f32_e32 v154, 0xbfb8aa3b, v185
	v_exp_f32_e32 v154, v154
	v_pk_mul_f32 v[214:215], v[62:63], v[198:199]
	s_mov_b32 s0, 0x9cd2000
	s_addk_i32 s4, 0x6000
	v_add_f32_e32 v154, 1.0, v154
	v_rcp_f32_e32 v193, v154
	v_mov_b32_e32 v154, v169
	v_lshlrev_b32_e32 v169, 16, v171
	v_pk_mul_f32 v[170:171], v[74:75], v[156:157]
	v_pk_mul_f32 v[184:185], v[184:185], v[192:193]
	v_pk_mul_f32 v[192:193], v[80:81], v[154:155]
	v_mov_b32_e32 v154, v169
	v_pk_mul_f32 v[194:195], v[76:77], v[154:155]
	v_mov_b32_e32 v173, v171
	v_mov_b32_e32 v172, v195
	v_pk_add_f32 v[172:173], v[178:179], v[172:173]
	v_mov_b32_e32 v195, v170
	v_pk_add_f32 v[170:171], v[194:195], v[172:173]
	v_pk_mul_f32 v[196:197], v[76:77], v[168:169]
	v_mul_f32_e32 v167, 0xbfb8aa3b, v170
	v_exp_f32_e32 v167, v167
	v_pk_mul_f32 v[154:155], v[2:3], v[154:155]
	v_pk_mul_f32 v[156:157], v[62:63], v[156:157]
	v_lshl_add_u64 v[132:133], v[132:133], 0, s[40:41]
	v_add_f32_e32 v167, 1.0, v167
	v_rcp_f32_e32 v172, v167
	v_mul_f32_e32 v167, 0xbfb8aa3b, v171
	v_exp_f32_e32 v167, v167
	s_cmp_eq_u32 s4, 0x1e000
	v_add_f32_e32 v167, 1.0, v167
	v_rcp_f32_e32 v173, v167
	s_nop 0
	v_pk_mul_f32 v[170:171], v[170:171], v[172:173]
	s_nop 0
	v_pk_mul_f32 v[172:173], v[94:95], v[170:171]
	v_pk_mul_f32 v[178:179], v[96:97], v[170:171]
	v_add_f32_e32 v167, v202, v172
	v_add_f32_e32 v167, v167, v173
	v_mul_f32_e32 v243, 0x3db504f3, v167
	v_add_f32_e32 v167, v203, v178
	v_add_f32_e32 v167, v167, v179
	v_pk_mul_f32 v[178:179], v[86:87], v[170:171]
	v_mul_f32_e32 v239, 0x3db504f3, v167
	v_add_f32_e32 v167, v204, v178
	v_pk_fma_f32 v[172:173], v[16:17], v[170:171], v[190:191] op_sel_hi:[1,0,1]
	v_add_f32_e32 v167, v167, v179
	v_pk_mul_f32 v[178:179], v[88:89], v[170:171]
	v_pk_fma_f32 v[188:189], v[18:19], v[170:171], v[188:189] op_sel_hi:[1,0,1]
	v_pk_fma_f32 v[172:173], v[28:29], v[170:171], v[172:173] op_sel:[0,1,0]
	v_mul_f32_e32 v237, 0x3db504f3, v167
	v_add_f32_e32 v167, v208, v178
	v_pk_fma_f32 v[188:189], v[30:31], v[170:171], v[188:189] op_sel:[0,1,0]
	v_add_co_u32_e32 v178, vcc, s96, v174
	v_add_f32_e32 v167, v167, v179
	v_cvt_pk_bf16_f32 v172, v172, v173
	v_cvt_pk_bf16_f32 v173, v188, v189
	v_addc_co_u32_e32 v179, vcc, 0, v175, vcc
	global_store_dwordx2 v[178:179], v[172:173], off
	v_add_co_u32_e32 v178, vcc, s97, v174
	v_mul_f32_e32 v204, 0x3db504f3, v167
	s_nop 0
	v_addc_co_u32_e32 v179, vcc, 0, v175, vcc
	v_cvt_pk_bf16_f32 v167, v170, v171
	v_add_co_u32_e32 v170, vcc, s33, v174
	v_cvt_pk_bf16_f32 v172, v243, v239
	s_nop 0
	v_addc_co_u32_e32 v171, vcc, 0, v175, vcc
	global_store_dwordx2 v[170:171], v[166:167], off
	v_mov_b32_e32 v170, v192
	v_mov_b32_e32 v171, v200
	v_cvt_pk_bf16_f32 v173, v237, v204
	v_pk_mul_f32 v[166:167], v[74:75], v[198:199]
	v_pk_add_f32 v[170:171], v[66:67], v[170:171]
	v_mov_b32_e32 v200, v193
	global_store_dwordx2 v[178:179], v[172:173], off
	v_pk_add_f32 v[170:171], v[170:171], v[200:201]
	v_mov_b32_e32 v172, v197
	v_mov_b32_e32 v173, v167
	v_pk_add_f32 v[170:171], v[172:173], v[170:171]
	v_mov_b32_e32 v197, v166
	v_pk_add_f32 v[166:167], v[196:197], v[170:171]
	v_pk_fma_f32 v[174:175], v[58:59], v[184:185], 0 op_sel_hi:[1,0,0]
	v_mul_f32_e32 v170, 0xbfb8aa3b, v166
	v_mul_f32_e32 v171, 0xbfb8aa3b, v167
	v_exp_f32_e32 v170, v170
	v_exp_f32_e32 v171, v171
	v_pk_fma_f32 v[174:175], v[50:51], v[184:185], v[174:175] op_sel:[0,1,0]
	v_add_f32_e32 v170, 1.0, v170
	v_add_f32_e32 v171, 1.0, v171
	v_rcp_f32_e32 v170, v170
	v_rcp_f32_e32 v171, v171
	s_nop 0
	v_pk_mul_f32 v[192:193], v[166:167], v[170:171]
	v_pk_fma_f32 v[166:167], v[120:121], v[164:165], 0 op_sel_hi:[1,1,0]
	v_pk_fma_f32 v[170:171], v[20:21], v[164:165], 0 op_sel_hi:[1,1,0]
	v_pk_fma_f32 v[166:167], v[118:119], v[162:163], v[166:167]
	v_pk_fma_f32 v[170:171], v[52:53], v[162:163], v[170:171]
	v_pk_fma_f32 v[166:167], v[116:117], v[168:169], v[166:167]
	v_pk_fma_f32 v[170:171], v[12:13], v[168:169], v[170:171]
	v_pk_fma_f32 v[188:189], v[114:115], v[198:199], v[166:167]
	v_pk_fma_f32 v[166:167], v[24:25], v[184:185], 0 op_sel_hi:[1,0,0]
	v_pk_fma_f32 v[178:179], v[36:37], v[198:199], v[170:171]
	v_pk_fma_f32 v[166:167], v[44:45], v[184:185], v[166:167] op_sel:[0,1,0]
	v_pk_fma_f32 v[170:171], v[56:57], v[184:185], 0 op_sel_hi:[1,0,0]
	v_pk_fma_f32 v[166:167], v[16:17], v[192:193], v[166:167] op_sel_hi:[1,0,1]
	v_pk_fma_f32 v[170:171], v[48:49], v[184:185], v[170:171] op_sel:[0,1,0]
	v_pk_fma_f32 v[166:167], v[28:29], v[192:193], v[166:167] op_sel:[0,1,0]
	v_pk_fma_f32 v[170:171], v[40:41], v[192:193], v[170:171] op_sel_hi:[1,0,1]
	v_cvt_pk_bf16_f32 v194, v166, v167
	v_lshl_add_u64 v[166:167], s[58:59], 0, v[130:131]
	v_pk_fma_f32 v[170:171], v[32:33], v[192:193], v[170:171] op_sel:[0,1,0]
	v_add_co_u32_e32 v200, vcc, s96, v166
	v_pk_mul_f32 v[190:191], v[170:171], s[38:39] op_sel_hi:[1,0]
	v_pk_fma_f32 v[170:171], v[128:129], v[164:165], 0 op_sel_hi:[1,1,0]
	v_addc_co_u32_e32 v201, vcc, 0, v167, vcc
	v_pk_fma_f32 v[170:171], v[126:127], v[162:163], v[170:171]
	v_add_co_u32_e32 v202, vcc, s97, v166
	v_pk_fma_f32 v[170:171], v[124:125], v[168:169], v[170:171]
	s_nop 0
	v_addc_co_u32_e32 v203, vcc, 0, v167, vcc
	v_pk_fma_f32 v[172:173], v[122:123], v[198:199], v[170:171]
	v_pk_fma_f32 v[170:171], v[26:27], v[184:185], 0 op_sel_hi:[1,0,0]
	v_add_co_u32_e32 v208, vcc, s33, v166
	v_pk_fma_f32 v[170:171], v[46:47], v[184:185], v[170:171] op_sel:[0,1,0]
	v_cvt_pk_bf16_f32 v184, v184, v185
	v_cvt_pk_bf16_f32 v185, v192, v193
	v_addc_co_u32_e32 v209, vcc, 0, v167, vcc
	global_store_dwordx2 v[208:209], v[184:185], off offset:1024
	v_mov_b32_e32 v184, v159
	v_mov_b32_e32 v185, v161
	v_pk_add_f32 v[184:185], v[64:65], v[184:185]
	v_mov_b32_e32 v159, v160
	v_pk_add_f32 v[160:161], v[158:159], v[184:185]
	v_mov_b32_e32 v158, v155
	v_mov_b32_e32 v159, v157
	v_pk_add_f32 v[158:159], v[66:67], v[158:159]
	v_mov_b32_e32 v155, v156
	v_pk_add_f32 v[158:159], v[154:155], v[158:159]
	v_lshlrev_b32_e32 v154, 16, v180
	v_mov_b32_e32 v156, v154
	v_mov_b32_e32 v157, v164
	v_pk_fma_f32 v[170:171], v[18:19], v[192:193], v[170:171] op_sel_hi:[1,0,1]
	v_pk_fma_f32 v[174:175], v[42:43], v[192:193], v[174:175] op_sel_hi:[1,0,1]
	v_pk_mul_f32 v[184:185], v[108:109], v[156:157]
	v_and_b32_e32 v156, 0xffff0000, v180
	v_pk_fma_f32 v[196:197], v[30:31], v[192:193], v[170:171] op_sel:[0,1,0]
	v_pk_fma_f32 v[174:175], v[34:35], v[192:193], v[174:175] op_sel:[0,1,0]
	v_mov_b32_e32 v192, v156
	v_mov_b32_e32 v193, v162
	v_pk_mul_f32 v[192:193], v[112:113], v[192:193]
	v_mov_b32_e32 v212, v185
	v_mov_b32_e32 v213, v193
	v_pk_add_f32 v[160:161], v[212:213], v[160:161]
	v_mov_b32_e32 v185, v192
	v_pk_fma_f32 v[170:171], v[22:23], v[164:165], 0 op_sel_hi:[1,1,0]
	v_pk_add_f32 v[160:161], v[184:185], v[160:161]
	v_pk_fma_f32 v[170:171], v[54:55], v[162:163], v[170:171]
	v_mul_f32_e32 v163, 0xbfb8aa3b, v160
	v_exp_f32_e32 v163, v163
	v_pk_mul_f32 v[174:175], v[174:175], s[38:39] op_sel_hi:[1,0]
	v_cvt_pk_bf16_f32 v195, v196, v197
	global_store_dwordx2 v[200:201], v[194:195], off offset:1024
	v_add_f32_e32 v163, 1.0, v163
	v_rcp_f32_e32 v184, v163
	v_mul_f32_e32 v163, 0xbfb8aa3b, v161
	v_exp_f32_e32 v163, v163
	v_cvt_pk_bf16_f32 v194, v190, v191
	v_cvt_pk_bf16_f32 v195, v174, v175
	global_store_dwordx2 v[202:203], v[194:195], off offset:1024
	v_add_f32_e32 v163, 1.0, v163
	v_rcp_f32_e32 v185, v163
	v_pk_mul_f32 v[194:195], v[100:101], v[164:165]
	v_lshlrev_b32_e32 v155, 16, v182
	v_and_b32_e32 v157, 0xffff0000, v182
	v_pk_mul_f32 v[160:161], v[160:161], v[184:185]
	v_mov_b32_e32 v212, v195
	v_pk_mul_f32 v[184:185], v[90:91], v[160:161]
	v_mov_b32_e32 v213, v211
	v_add_f32_e32 v163, 0, v184
	v_add_f32_e32 v163, v163, v185
	v_pk_mul_f32 v[184:185], v[92:93], v[160:161]
	v_pk_mul_f32 v[196:197], v[106:107], v[154:155]
	v_add_f32_e32 v165, 0, v184
	v_add_f32_e32 v165, v165, v185
	v_pk_fma_f32 v[184:185], v[24:25], v[160:161], 0 op_sel_hi:[1,0,0]
	v_pk_add_f32 v[212:213], v[64:65], v[212:213]
	v_pk_fma_f32 v[192:193], v[44:45], v[160:161], v[184:185] op_sel:[0,1,0]
	v_pk_mul_f32 v[184:185], v[82:83], v[160:161]
	v_mov_b32_e32 v195, v210
	v_add_f32_e32 v180, 0, v184
	v_add_f32_e32 v218, v180, v185
	v_pk_mul_f32 v[184:185], v[84:85], v[160:161]
	v_pk_add_f32 v[194:195], v[212:213], v[194:195]
	v_add_f32_e32 v180, 0, v184
	v_add_f32_e32 v219, v180, v185
	v_pk_fma_f32 v[184:185], v[26:27], v[160:161], 0 op_sel_hi:[1,0,0]
	v_cvt_pk_bf16_f32 v180, v160, v161
	v_pk_fma_f32 v[184:185], v[46:47], v[160:161], v[184:185] op_sel:[0,1,0]
	v_pk_mul_f32 v[160:161], v[110:111], v[156:157]
	v_mov_b32_e32 v210, v196
	v_mov_b32_e32 v211, v160
	v_pk_add_f32 v[194:195], v[194:195], v[210:211]
	v_mov_b32_e32 v160, v197
	v_pk_add_f32 v[160:161], v[194:195], v[160:161]
	v_lshlrev_b32_e32 v212, 16, v181
	v_mul_f32_e32 v182, 0xbfb8aa3b, v160
	v_exp_f32_e32 v182, v182
	v_lshlrev_b32_e32 v213, 16, v183
	v_mov_b32_e32 v196, v212
	v_mov_b32_e32 v197, v168
	v_add_f32_e32 v182, 1.0, v182
	v_rcp_f32_e32 v194, v182
	v_mul_f32_e32 v182, 0xbfb8aa3b, v161
	v_exp_f32_e32 v182, v182
	v_mov_b32_e32 v183, v198
	v_pk_mul_f32 v[196:197], v[76:77], v[196:197]
	v_pk_fma_f32 v[170:171], v[14:15], v[168:169], v[170:171]
	v_add_f32_e32 v182, 1.0, v182
	v_rcp_f32_e32 v195, v182
	v_mov_b32_e32 v182, v220
	v_pk_mul_f32 v[182:183], v[74:75], v[182:183]
	v_mov_b32_e32 v216, v197
	v_mov_b32_e32 v217, v183
	v_pk_add_f32 v[158:159], v[216:217], v[158:159]
	v_mov_b32_e32 v197, v182
	v_pk_add_f32 v[158:159], v[196:197], v[158:159]
	v_pk_mul_f32 v[160:161], v[160:161], v[194:195]
	v_pk_mul_f32 v[194:195], v[2:3], v[168:169]
	v_mul_f32_e32 v169, 0xbfb8aa3b, v158
	v_exp_f32_e32 v169, v169
	v_pk_mul_f32 v[210:211], v[6:7], v[212:213]
	v_pk_fma_f32 v[170:171], v[38:39], v[198:199], v[170:171]
	v_mov_b32_e32 v199, v220
	v_add_f32_e32 v169, 1.0, v169
	v_rcp_f32_e32 v182, v169
	v_mul_f32_e32 v169, 0xbfb8aa3b, v159
	v_exp_f32_e32 v169, v169
	v_pk_mul_f32 v[198:199], v[78:79], v[198:199]
	v_mov_b32_e32 v228, v157
	v_lshl_add_u64 v[130:131], v[130:131], 0, s[40:41]
	v_add_f32_e32 v169, 1.0, v169
	v_rcp_f32_e32 v183, v169
	v_mov_b32_e32 v169, v212
	v_pk_mul_f32 v[168:169], v[80:81], v[168:169]
	v_pk_mul_f32 v[158:159], v[158:159], v[182:183]
	s_nop 0
	v_pk_mul_f32 v[182:183], v[94:95], v[158:159]
	v_pk_fma_f32 v[184:185], v[18:19], v[158:159], v[184:185] op_sel_hi:[1,0,1]
	v_add_f32_e32 v163, v163, v182
	v_add_f32_e32 v163, v163, v183
	v_pk_fma_f32 v[182:183], v[16:17], v[158:159], v[192:193] op_sel_hi:[1,0,1]
	v_pk_mul_f32 v[192:193], v[96:97], v[158:159]
	v_mul_f32_e32 v246, 0x3db504f3, v163
	v_add_f32_e32 v163, v165, v192
	v_add_f32_e32 v163, v163, v193
	v_pk_mul_f32 v[192:193], v[86:87], v[158:159]
	v_mul_f32_e32 v242, 0x3db504f3, v163
	v_add_f32_e32 v163, v218, v192
	v_add_f32_e32 v163, v163, v193
	v_pk_mul_f32 v[192:193], v[88:89], v[158:159]
	v_mul_f32_e32 v241, 0x3db504f3, v163
	v_add_f32_e32 v163, v219, v192
	v_pk_fma_f32 v[182:183], v[28:29], v[158:159], v[182:183] op_sel:[0,1,0]
	v_pk_fma_f32 v[184:185], v[30:31], v[158:159], v[184:185] op_sel:[0,1,0]
	v_add_f32_e32 v163, v163, v193
	v_cvt_pk_bf16_f32 v181, v158, v159
	v_mul_f32_e32 v238, 0x3db504f3, v163
	v_cvt_pk_bf16_f32 v182, v182, v183
	v_cvt_pk_bf16_f32 v183, v184, v185
	global_store_dwordx2 v[208:209], v[180:181], off offset:2048
	v_mov_b32_e32 v180, v195
	v_mov_b32_e32 v181, v215
	global_store_dwordx2 v[200:201], v[182:183], off offset:2048
	v_cvt_pk_bf16_f32 v182, v246, v242
	v_cvt_pk_bf16_f32 v183, v241, v238
	v_pk_mul_f32 v[158:159], v[10:11], v[220:221]
	v_pk_add_f32 v[180:181], v[66:67], v[180:181]
	v_mov_b32_e32 v195, v214
	global_store_dwordx2 v[202:203], v[182:183], off offset:2048
	v_pk_add_f32 v[180:181], v[180:181], v[194:195]
	v_mov_b32_e32 v182, v210
	v_mov_b32_e32 v183, v158
	v_pk_add_f32 v[180:181], v[180:181], v[182:183]
	v_mov_b32_e32 v158, v211
	v_pk_add_f32 v[158:159], v[180:181], v[158:159]
	v_pk_fma_f32 v[184:185], v[58:59], v[160:161], 0 op_sel_hi:[1,0,0]
	v_mul_f32_e32 v163, 0xbfb8aa3b, v158
	v_exp_f32_e32 v163, v163
	v_pk_fma_f32 v[184:185], v[50:51], v[160:161], v[184:185] op_sel:[0,1,0]
	v_mov_b32_e32 v165, v154
	v_pk_mul_f32 v[164:165], v[98:99], v[164:165]
	v_add_f32_e32 v163, 1.0, v163
	v_rcp_f32_e32 v180, v163
	v_mul_f32_e32 v163, 0xbfb8aa3b, v159
	v_exp_f32_e32 v163, v163
	s_nop 0
	v_add_f32_e32 v163, 1.0, v163
	v_rcp_f32_e32 v181, v163
	v_mov_b32_e32 v163, v156
	v_pk_mul_f32 v[162:163], v[102:103], v[162:163]
	v_pk_mul_f32 v[158:159], v[158:159], v[180:181]
	v_pk_fma_f32 v[180:181], v[120:121], v[154:155], 0 op_sel_hi:[1,1,0]
	v_pk_fma_f32 v[184:185], v[42:43], v[158:159], v[184:185] op_sel_hi:[1,0,1]
	v_pk_fma_f32 v[180:181], v[118:119], v[156:157], v[180:181]
	v_pk_fma_f32 v[184:185], v[34:35], v[158:159], v[184:185] op_sel:[0,1,0]
	v_pk_fma_f32 v[180:181], v[116:117], v[212:213], v[180:181]
	v_pk_mul_f32 v[184:185], v[184:185], s[38:39] op_sel_hi:[1,0]
	v_pk_fma_f32 v[194:195], v[114:115], v[220:221], v[180:181]
	v_pk_fma_f32 v[180:181], v[24:25], v[160:161], 0 op_sel_hi:[1,0,0]
	s_nop 0
	v_pk_fma_f32 v[180:181], v[44:45], v[160:161], v[180:181] op_sel:[0,1,0]
	s_nop 0
	v_pk_fma_f32 v[180:181], v[16:17], v[158:159], v[180:181] op_sel_hi:[1,0,1]
	s_nop 0
	v_pk_fma_f32 v[210:211], v[28:29], v[158:159], v[180:181] op_sel:[0,1,0]
	v_pk_fma_f32 v[180:181], v[20:21], v[154:155], 0 op_sel_hi:[1,1,0]
	v_cvt_pk_bf16_f32 v210, v210, v211
	v_pk_fma_f32 v[180:181], v[52:53], v[156:157], v[180:181]
	s_nop 0
	v_pk_fma_f32 v[180:181], v[12:13], v[212:213], v[180:181]
	s_nop 0
	v_pk_fma_f32 v[192:193], v[36:37], v[220:221], v[180:181]
	v_pk_fma_f32 v[180:181], v[56:57], v[160:161], 0 op_sel_hi:[1,0,0]
	s_nop 0
	v_pk_fma_f32 v[180:181], v[48:49], v[160:161], v[180:181] op_sel:[0,1,0]
	s_nop 0
	v_pk_fma_f32 v[180:181], v[40:41], v[158:159], v[180:181] op_sel_hi:[1,0,1]
	s_nop 0
	v_pk_fma_f32 v[180:181], v[32:33], v[158:159], v[180:181] op_sel:[0,1,0]
	s_nop 0
	v_pk_mul_f32 v[196:197], v[180:181], s[38:39] op_sel_hi:[1,0]
	v_pk_fma_f32 v[180:181], v[128:129], v[154:155], 0 op_sel_hi:[1,1,0]
	s_nop 0
	v_pk_fma_f32 v[180:181], v[126:127], v[156:157], v[180:181]
	s_nop 0
	v_pk_fma_f32 v[180:181], v[124:125], v[212:213], v[180:181]
	s_nop 0
	v_pk_fma_f32 v[182:183], v[122:123], v[220:221], v[180:181]
	v_pk_fma_f32 v[180:181], v[26:27], v[160:161], 0 op_sel_hi:[1,0,0]
	s_nop 0
	v_pk_fma_f32 v[180:181], v[46:47], v[160:161], v[180:181] op_sel:[0,1,0]
	v_cvt_pk_bf16_f32 v160, v160, v161
	v_pk_fma_f32 v[180:181], v[18:19], v[158:159], v[180:181] op_sel_hi:[1,0,1]
	v_cvt_pk_bf16_f32 v161, v158, v159
	v_pk_fma_f32 v[214:215], v[30:31], v[158:159], v[180:181] op_sel:[0,1,0]
	global_store_dwordx2 v[208:209], v[160:161], off offset:3072
	v_mov_b32_e32 v208, v164
	v_mov_b32_e32 v209, v162
	v_cvt_pk_bf16_f32 v211, v214, v215
	v_pk_add_f32 v[208:209], v[64:65], v[208:209]
	v_mov_b32_e32 v162, v165
	global_store_dwordx2 v[200:201], v[210:211], off offset:3072
	v_cvt_pk_bf16_f32 v200, v196, v197
	v_cvt_pk_bf16_f32 v201, v184, v185
	s_waitcnt vmcnt(22)
	v_lshlrev_b32_e32 v161, 16, v187
	v_and_b32_e32 v159, 0xffff0000, v187
	v_mov_b32_e32 v160, v213
	v_mov_b32_e32 v158, v221
	v_pk_add_f32 v[218:219], v[208:209], v[162:163]
	v_mov_b32_e32 v162, v168
	v_mov_b32_e32 v163, v198
	global_store_dwordx2 v[202:203], v[200:201], off offset:3072
	v_pk_mul_f32 v[200:201], v[6:7], v[160:161]
	v_pk_mul_f32 v[202:203], v[10:11], v[158:159]
	v_pk_add_f32 v[162:163], v[66:67], v[162:163]
	v_mov_b32_e32 v198, v169
	v_pk_add_f32 v[162:163], v[162:163], v[198:199]
	v_mov_b32_e32 v164, v200
	v_mov_b32_e32 v165, v202
	v_pk_add_f32 v[162:163], v[162:163], v[164:165]
	v_mov_b32_e32 v202, v201
	v_pk_add_f32 v[162:163], v[162:163], v[202:203]
	v_pk_fma_f32 v[180:181], v[22:23], v[154:155], 0 op_sel_hi:[1,1,0]
	v_mul_f32_e32 v164, 0xbfb8aa3b, v162
	v_mul_f32_e32 v165, 0xbfb8aa3b, v163
	v_exp_f32_e32 v164, v164
	v_exp_f32_e32 v165, v165
	v_pk_fma_f32 v[180:181], v[54:55], v[156:157], v[180:181]
	v_and_b32_e32 v187, 0xffff0000, v186
	v_pk_fma_f32 v[180:181], v[14:15], v[212:213], v[180:181]
	v_pk_mul_f32 v[198:199], v[80:81], v[212:213]
	v_lshlrev_b32_e32 v212, 16, v186
	v_mov_b32_e32 v213, v187
	v_pk_fma_f32 v[180:181], v[38:39], v[220:221], v[180:181]
	v_add_f32_e32 v164, 1.0, v164
	v_add_f32_e32 v165, 1.0, v165
	v_pk_mul_f32 v[200:201], v[78:79], v[220:221]
	v_pk_mov_b32 v[220:221], v[154:155], v[212:213] op_sel:[1,0]
	v_mov_b32_e32 v229, v187
	v_rcp_f32_e32 v164, v164
	v_rcp_f32_e32 v165, v165
	v_pk_mul_f32 v[222:223], v[106:107], v[220:221]
	v_pk_mul_f32 v[224:225], v[110:111], v[228:229]
	v_mov_b32_e32 v226, v222
	v_mov_b32_e32 v227, v224
	v_pk_add_f32 v[218:219], v[218:219], v[226:227]
	v_mov_b32_e32 v224, v223
	v_pk_add_f32 v[218:219], v[218:219], v[224:225]
	v_pk_mul_f32 v[202:203], v[162:163], v[164:165]
	s_waitcnt vmcnt(22)
	v_lshlrev_b32_e32 v164, 16, v70
	v_and_b32_e32 v162, 0xffff0000, v70
	v_mul_f32_e32 v70, 0xbfb8aa3b, v218
	v_exp_f32_e32 v70, v70
	v_pk_mul_f32 v[216:217], v[94:95], v[202:203]
	s_waitcnt vmcnt(21)
	v_lshlrev_b32_e32 v165, 16, v176
	v_and_b32_e32 v163, 0xffff0000, v176
	v_add_f32_e32 v70, 1.0, v70
	v_rcp_f32_e32 v222, v70
	v_mul_f32_e32 v70, 0xbfb8aa3b, v219
	v_exp_f32_e32 v70, v70
	v_pk_mul_f32 v[214:215], v[96:97], v[202:203]
	v_pk_mul_f32 v[210:211], v[86:87], v[202:203]
	v_pk_mul_f32 v[208:209], v[88:89], v[202:203]
	v_add_f32_e32 v70, 1.0, v70
	v_rcp_f32_e32 v223, v70
	v_cvt_pk_bf16_f32 v169, v202, v203
	v_and_b32_e32 v186, 16, v186
	v_pk_mov_b32 v[250:251], v[186:187], v[162:163] op_sel:[1,0]
	v_pk_mul_f32 v[218:219], v[218:219], v[222:223]
	s_nop 0
	v_pk_mul_f32 v[222:223], v[90:91], v[218:219]
	v_pk_mul_f32 v[224:225], v[82:83], v[218:219]
	v_add_f32_e32 v70, 0, v222
	v_add_f32_e32 v70, v223, v70
	v_pk_mul_f32 v[222:223], v[92:93], v[218:219]
	v_add_f32_e32 v176, 0, v224
	v_add_f32_e32 v168, 0, v222
	v_add_f32_e32 v70, v216, v70
	v_add_f32_e32 v168, v223, v168
	v_pk_fma_f32 v[222:223], v[24:25], v[218:219], 0 op_sel_hi:[1,0,0]
	v_add_f32_e32 v176, v225, v176
	v_pk_mul_f32 v[224:225], v[84:85], v[218:219]
	v_add_f32_e32 v70, v217, v70
	v_pk_fma_f32 v[222:223], v[44:45], v[218:219], v[222:223] op_sel:[0,1,0]
	v_add_f32_e32 v224, 0, v224
	v_mul_f32_e32 v248, 0x3db504f3, v70
	v_add_f32_e32 v70, v214, v168
	v_add_f32_e32 v226, v225, v224
	v_pk_fma_f32 v[224:225], v[26:27], v[218:219], 0 op_sel_hi:[1,0,0]
	v_pk_fma_f32 v[216:217], v[16:17], v[202:203], v[222:223] op_sel_hi:[1,0,1]
	v_add_f32_e32 v70, v215, v70
	v_add_co_u32_e32 v222, vcc, s0, v166
	v_pk_fma_f32 v[224:225], v[46:47], v[218:219], v[224:225] op_sel:[0,1,0]
	v_mul_f32_e32 v245, 0x3db504f3, v70
	v_add_f32_e32 v70, v210, v176
	v_addc_co_u32_e32 v223, vcc, 0, v167, vcc
	s_mov_b32 s0, 0xacd2000
	v_add_f32_e32 v70, v211, v70
	v_pk_fma_f32 v[210:211], v[18:19], v[202:203], v[224:225] op_sel_hi:[1,0,1]
	v_add_co_u32_e32 v224, vcc, s0, v166
	s_mov_b32 s0, 0xccd2000
	s_nop 0
	v_addc_co_u32_e32 v225, vcc, 0, v167, vcc
	v_mul_f32_e32 v244, 0x3db504f3, v70
	v_add_f32_e32 v70, v208, v226
	v_add_co_u32_e32 v226, vcc, s0, v166
	v_mov_b32_e32 v166, v154
	s_nop 0
	v_addc_co_u32_e32 v227, vcc, 0, v167, vcc
	v_mov_b32_e32 v167, v156
	v_pk_fma_f32 v[166:167], v[60:61], v[166:167], v[64:65]
	v_mov_b32_e32 v156, v155
	v_pk_fma_f32 v[154:155], v[0:1], v[156:157], v[166:167]
	v_mov_b32_e32 v156, v164
	v_pk_fma_f32 v[154:155], v[4:5], v[212:213], v[154:155]
	v_mov_b32_e32 v157, v162
	v_add_f32_e32 v70, v209, v70
	v_pk_fma_f32 v[154:155], v[8:9], v[156:157], v[154:155]
	v_mul_f32_e32 v240, 0x3db504f3, v70
	v_mul_f32_e32 v70, 0xbfb8aa3b, v154
	v_exp_f32_e32 v70, v70
	v_pk_fma_f32 v[216:217], v[28:29], v[202:203], v[216:217] op_sel:[0,1,0]
	v_pk_fma_f32 v[202:203], v[30:31], v[202:203], v[210:211] op_sel:[0,1,0]
	v_cvt_pk_bf16_f32 v168, v218, v219
	v_add_f32_e32 v70, 1.0, v70
	v_rcp_f32_e32 v156, v70
	v_mul_f32_e32 v70, 0xbfb8aa3b, v155
	v_exp_f32_e32 v70, v70
	v_cvt_pk_bf16_f32 v209, v202, v203
	v_cvt_pk_bf16_f32 v202, v248, v245
	v_cvt_pk_bf16_f32 v203, v244, v240
	v_add_f32_e32 v70, 1.0, v70
	v_rcp_f32_e32 v157, v70
	global_store_dwordx2 v[226:227], v[168:169], off
	v_lshlrev_b32_e32 v169, 16, v177
	v_lshlrev_b32_e32 v168, 16, v71
	v_and_b32_e32 v167, 0xffff0000, v177
	v_and_b32_e32 v166, 0xffff0000, v71
	v_cvt_pk_bf16_f32 v208, v216, v217
	global_store_dwordx2 v[224:225], v[202:203], off
	v_pk_mul_f32 v[202:203], v[154:155], v[156:157]
	v_pk_mov_b32 v[154:155], v[168:169], v[168:169] op_sel:[1,0]
	v_pk_mov_b32 v[156:157], v[166:167], v[166:167] op_sel:[1,0]
	global_store_dwordx2 v[222:223], v[208:209], off
	v_mov_b32_e32 v208, v161
	v_mov_b32_e32 v209, v155
	v_mov_b32_e32 v218, v159
	v_mov_b32_e32 v219, v157
	v_mov_b32_e32 v214, v198
	v_mov_b32_e32 v215, v200
	v_pk_mul_f32 v[210:211], v[6:7], v[208:209]
	v_pk_mul_f32 v[176:177], v[10:11], v[218:219]
	v_pk_add_f32 v[214:215], v[66:67], v[214:215]
	v_mov_b32_e32 v200, v199
	v_pk_add_f32 v[198:199], v[214:215], v[200:201]
	v_mov_b32_e32 v200, v210
	v_mov_b32_e32 v201, v176
	v_pk_add_f32 v[198:199], v[198:199], v[200:201]
	v_mov_b32_e32 v176, v211
	v_pk_add_f32 v[176:177], v[198:199], v[176:177]
	v_mov_b32_e32 v213, v164
	v_mul_f32_e32 v71, 0xbfb8aa3b, v176
	v_exp_f32_e32 v71, v71
	v_cvt_pk_bf16_f32 v70, v202, v203
	v_pk_mul_f32 v[160:161], v[80:81], v[160:161]
	v_pk_mul_f32 v[158:159], v[78:79], v[158:159]
	v_add_f32_e32 v71, 1.0, v71
	v_rcp_f32_e32 v198, v71
	v_mul_f32_e32 v71, 0xbfb8aa3b, v177
	v_exp_f32_e32 v71, v71
	s_nop 0
	v_add_f32_e32 v71, 1.0, v71
	v_rcp_f32_e32 v199, v71
	s_nop 0
	v_pk_mul_f32 v[200:201], v[176:177], v[198:199]
	v_pk_fma_f32 v[176:177], v[120:121], v[212:213], 0 op_sel_hi:[1,1,0]
	v_pk_fma_f32 v[198:199], v[58:59], v[202:203], 0 op_sel_hi:[1,0,0]
	v_pk_fma_f32 v[176:177], v[118:119], v[250:251], v[176:177]
	v_pk_fma_f32 v[198:199], v[50:51], v[202:203], v[198:199] op_sel:[0,1,0]
	v_pk_fma_f32 v[176:177], v[116:117], v[208:209], v[176:177]
	v_pk_fma_f32 v[198:199], v[42:43], v[200:201], v[198:199] op_sel_hi:[1,0,1]
	v_pk_fma_f32 v[214:215], v[114:115], v[218:219], v[176:177]
	v_pk_fma_f32 v[176:177], v[24:25], v[202:203], 0 op_sel_hi:[1,0,0]
	v_pk_fma_f32 v[198:199], v[34:35], v[200:201], v[198:199] op_sel:[0,1,0]
	v_pk_fma_f32 v[176:177], v[44:45], v[202:203], v[176:177] op_sel:[0,1,0]
	v_pk_mul_f32 v[198:199], v[198:199], s[38:39] op_sel_hi:[1,0]
	v_pk_fma_f32 v[176:177], v[16:17], v[200:201], v[176:177] op_sel_hi:[1,0,1]
	v_cvt_pk_bf16_f32 v71, v200, v201
	v_pk_fma_f32 v[252:253], v[28:29], v[200:201], v[176:177] op_sel:[0,1,0]
	v_pk_fma_f32 v[176:177], v[20:21], v[212:213], 0 op_sel_hi:[1,1,0]
	global_store_dwordx2 v[226:227], v[70:71], off offset:1024
	v_pk_fma_f32 v[176:177], v[52:53], v[250:251], v[176:177]
	v_pk_mul_f32 v[70:71], v[98:99], v[220:221]
	v_pk_fma_f32 v[176:177], v[12:13], v[208:209], v[176:177]
	v_pk_mul_f32 v[220:221], v[110:111], v[162:163]
	v_pk_fma_f32 v[210:211], v[36:37], v[218:219], v[176:177]
	v_pk_fma_f32 v[176:177], v[56:57], v[202:203], 0 op_sel_hi:[1,0,0]
	s_nop 0
	v_pk_fma_f32 v[176:177], v[48:49], v[202:203], v[176:177] op_sel:[0,1,0]
	s_nop 0
	v_pk_fma_f32 v[176:177], v[40:41], v[200:201], v[176:177] op_sel_hi:[1,0,1]
	s_nop 0
	v_pk_fma_f32 v[176:177], v[32:33], v[200:201], v[176:177] op_sel:[0,1,0]
	s_nop 0
	v_pk_mul_f32 v[216:217], v[176:177], s[38:39] op_sel_hi:[1,0]
	v_pk_fma_f32 v[176:177], v[128:129], v[212:213], 0 op_sel_hi:[1,1,0]
	s_nop 0
	v_pk_fma_f32 v[176:177], v[126:127], v[250:251], v[176:177]
	s_nop 0
	v_pk_fma_f32 v[176:177], v[124:125], v[208:209], v[176:177]
	s_nop 0
	v_pk_fma_f32 v[186:187], v[122:123], v[218:219], v[176:177]
	v_pk_fma_f32 v[176:177], v[26:27], v[202:203], 0 op_sel_hi:[1,0,0]
	s_nop 0
	v_pk_fma_f32 v[176:177], v[46:47], v[202:203], v[176:177] op_sel:[0,1,0]
	v_cvt_pk_bf16_f32 v202, v252, v253
	v_pk_fma_f32 v[176:177], v[18:19], v[200:201], v[176:177] op_sel_hi:[1,0,1]
	v_mov_b32_e32 v252, v70
	v_pk_fma_f32 v[230:231], v[30:31], v[200:201], v[176:177] op_sel:[0,1,0]
	v_pk_mul_f32 v[200:201], v[106:107], v[164:165]
	v_cvt_pk_bf16_f32 v203, v230, v231
	global_store_dwordx2 v[222:223], v[202:203], off offset:1024
	v_cvt_pk_bf16_f32 v202, v216, v217
	v_cvt_pk_bf16_f32 v203, v198, v199
	global_store_dwordx2 v[224:225], v[202:203], off offset:1024
	v_pk_mul_f32 v[202:203], v[102:103], v[228:229]
	v_pk_mul_f32 v[228:229], v[6:7], v[168:169]
	v_mov_b32_e32 v253, v202
	v_pk_add_f32 v[252:253], v[64:65], v[252:253]
	v_mov_b32_e32 v202, v71
	v_pk_add_f32 v[70:71], v[252:253], v[202:203]
	v_mov_b32_e32 v202, v200
	v_mov_b32_e32 v203, v220
	v_pk_add_f32 v[70:71], v[70:71], v[202:203]
	v_mov_b32_e32 v220, v201
	v_pk_add_f32 v[70:71], v[70:71], v[220:221]
	v_mov_b32_e32 v220, v160
	v_mul_f32_e32 v155, 0xbfb8aa3b, v70
	v_exp_f32_e32 v155, v155
	v_mov_b32_e32 v221, v158
	v_pk_mul_f32 v[230:231], v[10:11], v[166:167]
	v_pk_add_f32 v[220:221], v[66:67], v[220:221]
	v_add_f32_e32 v155, 1.0, v155
	v_rcp_f32_e32 v200, v155
	v_mul_f32_e32 v155, 0xbfb8aa3b, v71
	v_mov_b32_e32 v158, v161
	v_exp_f32_e32 v155, v155
	v_pk_add_f32 v[158:159], v[220:221], v[158:159]
	v_mov_b32_e32 v160, v228
	v_mov_b32_e32 v161, v230
	v_pk_add_f32 v[158:159], v[158:159], v[160:161]
	v_mov_b32_e32 v230, v229
	v_pk_add_f32 v[158:159], v[158:159], v[230:231]
	v_add_f32_e32 v155, 1.0, v155
	v_mul_f32_e32 v160, 0xbfb8aa3b, v158
	v_mul_f32_e32 v161, 0xbfb8aa3b, v159
	v_exp_f32_e32 v160, v160
	v_exp_f32_e32 v161, v161
	v_rcp_f32_e32 v201, v155
	v_pk_fma_f32 v[176:177], v[22:23], v[212:213], 0 op_sel_hi:[1,1,0]
	v_add_f32_e32 v160, 1.0, v160
	v_add_f32_e32 v161, 1.0, v161
	v_pk_mul_f32 v[70:71], v[70:71], v[200:201]
	v_rcp_f32_e32 v160, v160
	v_rcp_f32_e32 v161, v161
	v_pk_mul_f32 v[200:201], v[90:91], v[70:71]
	v_pk_mul_f32 v[202:203], v[82:83], v[70:71]
	v_add_f32_e32 v155, 0, v200
	v_add_f32_e32 v155, v201, v155
	v_pk_mul_f32 v[200:201], v[92:93], v[70:71]
	v_pk_mul_f32 v[158:159], v[158:159], v[160:161]
	v_add_f32_e32 v157, 0, v200
	v_add_f32_e32 v157, v201, v157
	v_pk_fma_f32 v[200:201], v[24:25], v[70:71], 0 op_sel_hi:[1,0,0]
	v_pk_mul_f32 v[160:161], v[94:95], v[158:159]
	v_pk_fma_f32 v[200:201], v[44:45], v[70:71], v[200:201] op_sel:[0,1,0]
	v_add_f32_e32 v155, v160, v155
	v_add_f32_e32 v202, 0, v202
	v_add_f32_e32 v155, v161, v155
	v_pk_fma_f32 v[160:161], v[16:17], v[158:159], v[200:201] op_sel_hi:[1,0,1]
	v_pk_mul_f32 v[200:201], v[96:97], v[158:159]
	v_add_f32_e32 v252, v203, v202
	v_pk_mul_f32 v[202:203], v[84:85], v[70:71]
	v_mul_f32_e32 v249, 0x3db504f3, v155
	v_add_f32_e32 v155, v200, v157
	v_add_f32_e32 v202, 0, v202
	v_add_f32_e32 v155, v201, v155
	v_pk_mul_f32 v[200:201], v[86:87], v[158:159]
	v_add_f32_e32 v253, v203, v202
	v_pk_fma_f32 v[202:203], v[26:27], v[70:71], 0 op_sel_hi:[1,0,0]
	v_mul_f32_e32 v247, 0x3db504f3, v155
	v_add_f32_e32 v155, v200, v252
	v_pk_fma_f32 v[202:203], v[46:47], v[70:71], v[202:203] op_sel:[0,1,0]
	v_add_f32_e32 v155, v201, v155
	v_pk_mul_f32 v[200:201], v[88:89], v[158:159]
	v_mul_f32_e32 v229, 0x3db504f3, v155
	v_add_f32_e32 v155, v200, v253
	v_pk_fma_f32 v[202:203], v[18:19], v[158:159], v[202:203] op_sel_hi:[1,0,1]
	v_pk_fma_f32 v[160:161], v[28:29], v[158:159], v[160:161] op_sel:[0,1,0]
	v_pk_fma_f32 v[202:203], v[30:31], v[158:159], v[202:203] op_sel:[0,1,0]
	v_add_f32_e32 v155, v201, v155
	v_mul_f32_e32 v228, 0x3db504f3, v155
	v_cvt_pk_bf16_f32 v160, v160, v161
	v_cvt_pk_bf16_f32 v161, v202, v203
	global_store_dwordx2 v[222:223], v[160:161], off offset:2048
	v_cvt_pk_bf16_f32 v160, v249, v247
	v_cvt_pk_bf16_f32 v161, v229, v228
	global_store_dwordx2 v[224:225], v[160:161], off offset:2048
	v_cvt_pk_bf16_f32 v70, v70, v71
	v_cvt_pk_bf16_f32 v71, v158, v159
	s_waitcnt vmcnt(28)
	v_lshlrev_b32_e32 v159, 16, v68
	v_and_b32_e32 v161, 0xffff0000, v68
	v_lshlrev_b32_e32 v155, 16, v69
	v_and_b32_e32 v157, 0xffff0000, v69
	v_pk_mul_f32 v[68:69], v[98:99], v[212:213]
	v_pk_mul_f32 v[200:201], v[102:103], v[250:251]
	v_mov_b32_e32 v158, v165
	v_mov_b32_e32 v160, v163
	v_mov_b32_e32 v212, v68
	v_mov_b32_e32 v213, v200
	global_store_dwordx2 v[226:227], v[70:71], off offset:2048
	v_pk_mul_f32 v[70:71], v[106:107], v[158:159]
	v_pk_mul_f32 v[202:203], v[110:111], v[160:161]
	v_pk_add_f32 v[212:213], v[64:65], v[212:213]
	v_mov_b32_e32 v200, v69
	v_pk_add_f32 v[68:69], v[212:213], v[200:201]
	v_mov_b32_e32 v200, v70
	v_mov_b32_e32 v201, v202
	v_pk_add_f32 v[68:69], v[68:69], v[200:201]
	v_mov_b32_e32 v202, v71
	v_pk_add_f32 v[68:69], v[68:69], v[202:203]
	v_pk_mul_f32 v[202:203], v[78:79], v[218:219]
	v_mul_f32_e32 v70, 0xbfb8aa3b, v68
	v_mul_f32_e32 v71, 0xbfb8aa3b, v69
	v_exp_f32_e32 v70, v70
	v_exp_f32_e32 v71, v71
	v_pk_fma_f32 v[176:177], v[54:55], v[250:251], v[176:177]
	v_mov_b32_e32 v213, v202
	v_add_f32_e32 v70, 1.0, v70
	v_add_f32_e32 v71, 1.0, v71
	v_rcp_f32_e32 v70, v70
	v_rcp_f32_e32 v71, v71
	v_pk_fma_f32 v[176:177], v[14:15], v[208:209], v[176:177]
	v_pk_mul_f32 v[200:201], v[6:7], v[154:155]
	v_pk_fma_f32 v[176:177], v[38:39], v[218:219], v[176:177]
	v_pk_mul_f32 v[68:69], v[68:69], v[70:71]
	v_pk_mul_f32 v[70:71], v[80:81], v[208:209]
	v_pk_mul_f32 v[208:209], v[10:11], v[156:157]
	v_mov_b32_e32 v212, v70
	v_pk_add_f32 v[212:213], v[66:67], v[212:213]
	v_mov_b32_e32 v202, v71
	v_pk_add_f32 v[70:71], v[212:213], v[202:203]
	v_mov_b32_e32 v202, v200
	v_mov_b32_e32 v203, v208
	v_pk_add_f32 v[70:71], v[70:71], v[202:203]
	v_mov_b32_e32 v208, v201
	v_pk_add_f32 v[70:71], v[70:71], v[208:209]
	v_pk_fma_f32 v[208:209], v[58:59], v[68:69], 0 op_sel_hi:[1,0,0]
	v_mul_f32_e32 v200, 0xbfb8aa3b, v70
	v_mul_f32_e32 v201, 0xbfb8aa3b, v71
	v_exp_f32_e32 v200, v200
	v_exp_f32_e32 v201, v201
	v_pk_fma_f32 v[208:209], v[50:51], v[68:69], v[208:209] op_sel:[0,1,0]
	v_add_f32_e32 v200, 1.0, v200
	v_add_f32_e32 v201, 1.0, v201
	v_rcp_f32_e32 v200, v200
	v_rcp_f32_e32 v201, v201
	s_nop 0
	v_pk_mul_f32 v[70:71], v[70:71], v[200:201]
	v_pk_fma_f32 v[200:201], v[120:121], v[158:159], 0 op_sel_hi:[1,1,0]
	v_pk_fma_f32 v[208:209], v[42:43], v[70:71], v[208:209] op_sel_hi:[1,0,1]
	v_pk_fma_f32 v[200:201], v[118:119], v[160:161], v[200:201]
	v_pk_fma_f32 v[208:209], v[34:35], v[70:71], v[208:209] op_sel:[0,1,0]
	v_pk_fma_f32 v[200:201], v[116:117], v[154:155], v[200:201]
	v_pk_mul_f32 v[208:209], v[208:209], s[38:39] op_sel_hi:[1,0]
	v_pk_fma_f32 v[218:219], v[114:115], v[156:157], v[200:201]
	v_pk_fma_f32 v[200:201], v[24:25], v[68:69], 0 op_sel_hi:[1,0,0]
	s_nop 0
	v_pk_fma_f32 v[200:201], v[44:45], v[68:69], v[200:201] op_sel:[0,1,0]
	s_nop 0
	v_pk_fma_f32 v[200:201], v[16:17], v[70:71], v[200:201] op_sel_hi:[1,0,1]
	s_nop 0
	v_pk_fma_f32 v[230:231], v[28:29], v[70:71], v[200:201] op_sel:[0,1,0]
	v_pk_fma_f32 v[200:201], v[20:21], v[158:159], 0 op_sel_hi:[1,1,0]
	v_cvt_pk_bf16_f32 v230, v230, v231
	v_pk_fma_f32 v[200:201], v[52:53], v[160:161], v[200:201]
	s_nop 0
	v_pk_fma_f32 v[200:201], v[12:13], v[154:155], v[200:201]
	s_nop 0
	v_pk_fma_f32 v[212:213], v[36:37], v[156:157], v[200:201]
	v_pk_fma_f32 v[200:201], v[56:57], v[68:69], 0 op_sel_hi:[1,0,0]
	s_nop 0
	v_pk_fma_f32 v[200:201], v[48:49], v[68:69], v[200:201] op_sel:[0,1,0]
	s_nop 0
	v_pk_fma_f32 v[200:201], v[40:41], v[70:71], v[200:201] op_sel_hi:[1,0,1]
	s_nop 0
	v_pk_fma_f32 v[200:201], v[32:33], v[70:71], v[200:201] op_sel:[0,1,0]
	s_nop 0
	v_pk_mul_f32 v[220:221], v[200:201], s[38:39] op_sel_hi:[1,0]
	v_pk_fma_f32 v[200:201], v[128:129], v[158:159], 0 op_sel_hi:[1,1,0]
	s_nop 0
	v_pk_fma_f32 v[200:201], v[126:127], v[160:161], v[200:201]
	s_nop 0
	v_pk_fma_f32 v[200:201], v[124:125], v[154:155], v[200:201]
	s_nop 0
	v_pk_fma_f32 v[202:203], v[122:123], v[156:157], v[200:201]
	v_pk_fma_f32 v[200:201], v[26:27], v[68:69], 0 op_sel_hi:[1,0,0]
	s_nop 0
	v_pk_fma_f32 v[200:201], v[46:47], v[68:69], v[200:201] op_sel:[0,1,0]
	v_cvt_pk_bf16_f32 v68, v68, v69
	v_pk_fma_f32 v[200:201], v[18:19], v[70:71], v[200:201] op_sel_hi:[1,0,1]
	v_cvt_pk_bf16_f32 v69, v70, v71
	v_pk_fma_f32 v[250:251], v[30:31], v[70:71], v[200:201] op_sel:[0,1,0]
	global_store_dwordx2 v[226:227], v[68:69], off offset:3072
	v_cvt_pk_bf16_f32 v231, v250, v251
	global_store_dwordx2 v[222:223], v[230:231], off offset:3072
	v_cvt_pk_bf16_f32 v222, v220, v221
	v_cvt_pk_bf16_f32 v223, v208, v209
	global_store_dwordx2 v[224:225], v[222:223], off offset:3072
	v_lshl_add_u64 v[222:223], s[58:59], 0, v[136:137]
	v_and_b32_e32 v224, 0xffffc000, v134
	v_bfe_u32 v225, v134, 9, 5
	v_lshl_or_b32 v224, v225, 4, v224
	v_bfe_u32 v225, v134, 4, 3
	v_lshl_or_b32 v224, v225, 11, v224
	v_cvt_pk_bf16_f32 v68, v243, v190
	v_cvt_pk_bf16_f32 v69, v246, v196
	v_cvt_pk_bf16_f32 v70, v248, v216
	v_cvt_pk_bf16_f32 v71, v249, v220
	s_nop 0
	global_store_dwordx4 v224, v[68:71], s[84:85]
	v_pk_fma_f32 v[200:201], v[22:23], v[158:159], 0 op_sel_hi:[1,1,0]
	v_lshl_add_u64 v[136:137], v[136:137], 0, 16
	v_pk_mov_b32 v[68:69], v[188:189], v[188:189] op_sel:[1,0]
	v_add_co_u32_e32 v188, vcc, s75, v222
	v_cvt_pk_bf16_f32 v68, v68, v69
	v_cvt_pk_bf16_f32 v69, v194, v195
	v_cvt_pk_bf16_f32 v70, v214, v215
	v_cvt_pk_bf16_f32 v71, v218, v219
	v_addc_co_u32_e32 v189, vcc, 0, v223, vcc
	v_lshl_add_u64 v[194:195], s[58:59], 0, v[134:135]
	global_store_dwordx4 v224, v[68:71], s[82:83]
	v_add_co_u32_e32 v188, vcc, s74, v194
	s_nop 0
	v_cvt_pk_bf16_f32 v68, v239, v191
	v_cvt_pk_bf16_f32 v69, v242, v197
	v_cvt_pk_bf16_f32 v70, v245, v217
	v_cvt_pk_bf16_f32 v71, v247, v221
	v_addc_co_u32_e32 v189, vcc, 0, v195, vcc
	global_store_dwordx4 v224, v[68:71], s[84:85] offset:512
	v_pk_fma_f32 v[200:201], v[54:55], v[160:161], v[200:201]
	v_cvt_pk_bf16_f32 v191, v192, v193
	v_pk_mov_b32 v[68:69], v[178:179], v[178:179] op_sel:[1,0]
	v_cvt_pk_bf16_f32 v192, v210, v211
	v_cvt_pk_bf16_f32 v190, v68, v69
	v_add_co_u32_e32 v68, vcc, s75, v194
	v_cvt_pk_bf16_f32 v193, v212, v213
	s_nop 0
	v_addc_co_u32_e32 v69, vcc, 0, v195, vcc
	v_pk_fma_f32 v[200:201], v[14:15], v[154:155], v[200:201]
	global_store_dwordx4 v224, v[190:193], s[82:83] offset:512
	v_pk_mov_b32 v[70:71], v[172:173], v[172:173] op_sel:[1,0]
	v_pk_fma_f32 v[200:201], v[38:39], v[156:157], v[200:201]
	v_cvt_pk_bf16_f32 v190, v237, v174
	v_cvt_pk_bf16_f32 v191, v241, v184
	v_cvt_pk_bf16_f32 v192, v244, v198
	v_cvt_pk_bf16_f32 v193, v229, v208
	global_store_dwordx4 v224, v[190:193], s[84:85] offset:1024
	v_cvt_pk_bf16_f32 v172, v204, v175
	v_cvt_pk_bf16_f32 v173, v238, v185
	v_cvt_pk_bf16_f32 v190, v70, v71
	v_cvt_pk_bf16_f32 v174, v240, v199
	v_cvt_pk_bf16_f32 v175, v228, v209
	v_pk_mov_b32 v[70:71], v[170:171], v[170:171] op_sel:[1,0]
	v_cvt_pk_bf16_f32 v191, v182, v183
	v_cvt_pk_bf16_f32 v192, v186, v187
	v_cvt_pk_bf16_f32 v193, v202, v203
	global_store_dwordx4 v224, v[172:175], s[84:85] offset:1536
	v_cvt_pk_bf16_f32 v170, v70, v71
	v_cvt_pk_bf16_f32 v171, v180, v181
	v_cvt_pk_bf16_f32 v172, v176, v177
	v_cvt_pk_bf16_f32 v173, v200, v201
	global_store_dwordx4 v224, v[190:193], s[82:83] offset:1024
	global_store_dwordx4 v224, v[170:173], s[82:83] offset:1536
	v_lshl_add_u64 v[134:135], v[134:135], 0, 16
	s_waitcnt vmcnt(37)
	v_mov_b64_e32 v[180:181], v[142:143]
	v_mov_b64_e32 v[170:171], v[138:139]
	v_mov_b64_e32 v[172:173], v[140:141]
	s_waitcnt vmcnt(36)
	v_mov_b64_e32 v[182:183], v[144:145]
	s_waitcnt vmcnt(35)
	v_mov_b64_e32 v[186:187], v[148:149]
	s_waitcnt vmcnt(34)
	v_mov_b64_e32 v[70:71], v[150:151]
	s_waitcnt vmcnt(33)
	v_mov_b64_e32 v[176:177], v[152:153]
	s_waitcnt vmcnt(32)
	v_mov_b64_e32 v[68:69], v[146:147]
	s_cbranch_scc0 .LBB0_407
	s_ashr_i32 s68, s79, 6
	v_bfe_u32 v56, v236, 5, 1
	s_or_b32 s0, s69, s25
	s_lshl_b32 s4, s68, 8
	v_lshlrev_b32_e32 v54, 3, v56
	v_lshlrev_b32_e32 v204, 11, v206
	s_ashr_i32 s1, s0, 31
	v_or_b32_e32 v50, s4, v54
	v_lshl_add_u64 v[36:37], s[12:13], 0, v[204:205]
	v_or_b32_e32 v0, s0, v206
	v_mov_b32_e32 v1, s1
	v_mov_b64_e32 v[2:3], s[8:9]
	v_lshlrev_b32_e32 v204, 11, v206
	v_ashrrev_i32_e32 v51, 31, v50
	v_lshlrev_b64 v[38:39], 10, v[0:1]
	v_mad_i64_i32 v[42:43], vcc, v0, s93, v[2:3]
	v_lshl_add_u64 v[0:1], v[50:51], 1, v[204:205]
	v_or_b32_e32 v40, 0x8000, v38
	v_mov_b32_e32 v41, v39
	s_mov_b64 vcc, 0x30000
	v_lshl_add_u64 v[52:53], s[34:35], 0, v[0:1]
	v_mov_b32_e32 v0, 0
	v_and_b32_e32 v55, 63, v236
	v_lshl_add_u64 v[44:45], s[10:11], 0, v[38:39]
	v_lshl_add_u64 v[46:47], s[10:11], 0, v[40:41]
	v_lshl_add_u64 v[48:49], v[42:43], 0, vcc
	s_mov_b32 s5, 0
	v_mov_b32_e32 v1, v0
	v_mov_b32_e32 v2, v0
	v_mov_b32_e32 v3, v0
	v_mov_b32_e32 v4, v0
	v_mov_b32_e32 v5, v0
	v_mov_b32_e32 v6, v0
	v_mov_b32_e32 v7, v0
	v_mov_b32_e32 v8, v0
	v_mov_b32_e32 v9, v0
	v_mov_b32_e32 v10, v0
	v_mov_b32_e32 v11, v0
	v_mov_b32_e32 v12, v0
	v_mov_b32_e32 v13, v0
	v_mov_b32_e32 v14, v0
	v_mov_b32_e32 v15, v0
	v_mov_b32_e32 v16, v0
	v_mov_b32_e32 v17, v0
	v_mov_b32_e32 v18, v0
	v_mov_b32_e32 v19, v0
	v_mov_b32_e32 v20, v0
	v_mov_b32_e32 v21, v0
	v_mov_b32_e32 v22, v0
	v_mov_b32_e32 v23, v0
	v_mov_b32_e32 v24, v0
	v_mov_b32_e32 v25, v0
	v_mov_b32_e32 v26, v0
	v_mov_b32_e32 v27, v0
	v_mov_b32_e32 v28, v0
	v_mov_b32_e32 v29, v0
	v_mov_b32_e32 v30, v0
	v_mov_b32_e32 v31, v0
	s_barrier

.LBB0_412:
	s_or_b64 exec, exec, s[66:67]
	s_waitcnt lgkmcnt(0)
	v_add_f32_e32 v0, v1, v0
	s_lshl_b32 s0, s79, 2
	v_mul_f32_e32 v0, 0x3fb8aa3b, v0
	s_and_b32 s36, s0, 0xffffff00
	s_lshl_b64 s[0:1], s[4:5], 14
	v_exp_f32_e32 v0, v0
	s_add_u32 s24, s84, s0
	s_addc_u32 s25, s85, s1
	s_add_u32 s0, s82, s0
	v_lshl_or_b32 v1, v55, 2, s36
	s_addc_u32 s1, s83, s1
	v_lshlrev_b32_e32 v204, 1, v54
	ds_write_b32 v1, v0 offset:8192
	v_lshl_add_u64 v[0:1], s[0:1], 0, v[204:205]
	v_lshlrev_b32_e32 v2, 7, v206
	v_mov_b32_e32 v3, v205
	v_lshl_add_u64 v[16:17], v[0:1], 0, v[2:3]
	v_lshl_add_u64 v[20:21], s[24:25], 0, v[204:205]
	s_mov_b32 s98, s24
	s_mov_b32 s99, s25
	s_mov_b32 s100, s0
	s_mov_b32 s101, s1
	v_and_b32_e32 v226, 3, v206
	v_lshlrev_b32_e32 v226, 9, v226
	v_lshrrev_b32_e32 v227, 2, v206
	v_lshl_or_b32 v226, v227, 4, v226
	v_lshl_or_b32 v226, v56, 11, v226
	v_add_u32_e32 v227, 0x1000, v226
	v_add_u32_e32 v228, 0x2000, v226
	v_add_u32_e32 v229, 0x3000, v226
	s_waitcnt lgkmcnt(0)
	s_barrier
	global_load_dwordx4 v[4:7], v226, s[100:101]
	global_load_dwordx4 v[8:11], v227, s[100:101]
	v_lshl_add_u64 v[22:23], v[20:21], 0, v[2:3]
	global_load_dwordx4 v[120:123], v226, s[98:99]
	global_load_dwordx4 v[12:15], v228, s[100:101]
	v_mov_b32_e32 v25, v205
	v_or_b32_e32 v24, 0x1000, v2
	v_lshl_add_u64 v[26:27], v[20:21], 0, v[24:25]
	global_load_dwordx4 v[116:119], v226, s[98:99] offset:128
	global_load_dwordx4 v[112:115], v227, s[98:99]
	global_load_dwordx4 v[108:111], v227, s[98:99] offset:128
	global_load_dwordx4 v[104:107], v228, s[98:99]
	s_nop 0
	global_load_dwordx4 v[16:19], v229, s[100:101]
	v_mov_b32_e32 v29, v205
	v_or_b32_e32 v28, 0x2000, v2
	v_or_b32_e32 v2, 0x3000, v2
	global_load_dwordx4 v[100:103], v228, s[98:99] offset:128
	v_lshl_add_u64 v[30:31], v[20:21], 0, v[28:29]
	v_lshl_add_u64 v[20:21], v[20:21], 0, v[2:3]
	global_load_dwordx4 v[96:99], v229, s[98:99]
	global_load_dwordx4 v[92:95], v229, s[98:99] offset:128
	global_load_dwordx4 v[80:83], v226, s[98:99] offset:256
	global_load_dwordx4 v[76:79], v227, s[98:99] offset:256
	global_load_dwordx4 v[68:71], v228, s[98:99] offset:256
	global_load_dwordx4 v[64:67], v229, s[98:99] offset:256
	global_load_dwordx4 v[88:91], v226, s[98:99] offset:384
	global_load_dwordx4 v[84:87], v227, s[98:99] offset:384
	global_load_dwordx4 v[72:75], v228, s[98:99] offset:384
	v_and_or_b32 v126, v236, 32, s36
	ds_read_b128 v[148:151], v126 offset:8192
	ds_read_b128 v[144:147], v126 offset:8208
	ds_read_b128 v[128:131], v126 offset:8256
	ds_read_b128 v[132:135], v126 offset:8272
	ds_read_b128 v[136:139], v126 offset:8320
	ds_read_b128 v[140:143], v126 offset:8336
	ds_read_b128 v[156:159], v126 offset:8384
	ds_read_b128 v[152:155], v126 offset:8400
	v_lshl_add_u64 v[160:161], v[0:1], 0, v[2:3]
	s_mul_i32 s0, s4, 0x8100
	s_mul_hi_i32 s1, s4, 0x8100
	s_add_u32 s0, s88, s0
	s_addc_u32 s1, s89, s1
	v_lshl_add_u64 v[208:209], s[0:1], 0, v[204:205]
	v_lshlrev_b32_e32 v204, 8, v206
	v_lshl_add_u64 v[208:209], v[208:209], 0, v[204:205]
	s_movk_i32 s0, 0x6000
	v_cmp_eq_u32_e64 s[4:5], 0, v206
	s_waitcnt vmcnt(18)
	v_lshlrev_b32_e32 v22, 16, v4
	v_and_b32_e32 v23, 0xffff0000, v4
	v_lshlrev_b32_e32 v4, 16, v5
	v_and_b32_e32 v5, 0xffff0000, v5
	s_waitcnt vmcnt(17)
	v_lshlrev_b32_e32 v30, 16, v8
	v_and_b32_e32 v31, 0xffff0000, v8
	v_lshlrev_b32_e32 v8, 16, v9
	v_and_b32_e32 v9, 0xffff0000, v9
	s_waitcnt lgkmcnt(7)
	v_pk_mul_f32 v[22:23], v[148:149], v[22:23]
	v_pk_mul_f32 v[32:33], v[150:151], v[4:5]
	v_cvt_pk_bf16_f32 v4, v22, v23
	s_waitcnt vmcnt(15)
	v_lshlrev_b32_e32 v22, 16, v12
	v_and_b32_e32 v23, 0xffff0000, v12
	s_waitcnt lgkmcnt(5)
	v_pk_mul_f32 v[8:9], v[130:131], v[8:9]
	v_lshlrev_b32_e32 v124, 16, v10
	v_cvt_pk_bf16_f32 v211, v8, v9
	s_waitcnt lgkmcnt(3)
	v_pk_mul_f32 v[8:9], v[136:137], v[22:23]
	v_and_b32_e32 v125, 0xffff0000, v10
	v_cvt_pk_bf16_f32 v214, v8, v9
	s_waitcnt vmcnt(10)
	v_lshlrev_b32_e32 v8, 16, v16
	v_and_b32_e32 v9, 0xffff0000, v16
	s_waitcnt lgkmcnt(1)
	v_pk_mul_f32 v[8:9], v[156:157], v[8:9]
	v_pk_mul_f32 v[124:125], v[132:133], v[124:125]
	v_cvt_pk_bf16_f32 v218, v8, v9
	v_lshl_add_u64 v[8:9], v[0:1], 0, v[24:25]
	v_cvt_pk_bf16_f32 v212, v124, v125
	global_load_dwordx4 v[124:127], v229, s[98:99] offset:384
	global_load_dwordx4 v[222:225], v226, s[100:101] offset:128
	global_load_dwordx4 v[200:203], v227, s[100:101] offset:128
	global_load_dwordx4 v[196:199], v228, s[100:101] offset:128
	global_load_dwordx4 v[192:195], v229, s[100:101] offset:128
	v_lshlrev_b32_e32 v26, 16, v6
	v_and_b32_e32 v27, 0xffff0000, v6
	v_lshlrev_b32_e32 v6, 16, v7
	v_and_b32_e32 v7, 0xffff0000, v7
	v_lshlrev_b32_e32 v10, 16, v11
	v_and_b32_e32 v11, 0xffff0000, v11
	v_pk_mul_f32 v[26:27], v[144:145], v[26:27]
	v_pk_mul_f32 v[34:35], v[146:147], v[6:7]
	v_cvt_pk_bf16_f32 v6, v26, v27
	v_lshlrev_b32_e32 v12, 16, v13
	v_and_b32_e32 v13, 0xffff0000, v13
	v_lshlrev_b32_e32 v26, 16, v14
	v_and_b32_e32 v27, 0xffff0000, v14
	v_pk_mul_f32 v[10:11], v[134:135], v[10:11]
	v_lshlrev_b32_e32 v14, 16, v15
	v_and_b32_e32 v15, 0xffff0000, v15
	v_lshl_add_u64 v[8:9], v[0:1], 0, v[28:29]
	v_cvt_pk_bf16_f32 v5, v32, v33
	v_cvt_pk_bf16_f32 v7, v34, v35
	v_pk_mul_f32 v[30:31], v[128:129], v[30:31]
	v_cvt_pk_bf16_f32 v213, v10, v11
	v_pk_mul_f32 v[10:11], v[138:139], v[12:13]
	v_pk_mul_f32 v[12:13], v[140:141], v[26:27]
	v_pk_mul_f32 v[14:15], v[142:143], v[14:15]
	global_load_dwordx4 v[188:191], v226, s[100:101] offset:256
	global_load_dwordx4 v[184:187], v227, s[100:101] offset:256
	global_load_dwordx4 v[180:183], v228, s[100:101] offset:256
	global_load_dwordx4 v[176:179], v229, s[100:101] offset:256
	v_cvt_pk_bf16_f32 v210, v30, v31
	v_cvt_pk_bf16_f32 v215, v10, v11
	v_cvt_pk_bf16_f32 v216, v12, v13
	v_cvt_pk_bf16_f32 v217, v14, v15
	v_lshlrev_b32_e32 v10, 16, v17
	v_and_b32_e32 v11, 0xffff0000, v17
	v_lshlrev_b32_e32 v12, 16, v18
	v_and_b32_e32 v13, 0xffff0000, v18
	v_lshlrev_b32_e32 v14, 16, v19
	v_and_b32_e32 v15, 0xffff0000, v19
	s_waitcnt vmcnt(15)
	v_mfma_f32_32x32x16_bf16 v[16:31], v[80:83], v[4:7], 0
	v_mul_f32_e64 v10, v158, v10
	v_mul_f32_e64 v11, v159, v11
	s_waitcnt lgkmcnt(0)
	v_mul_f32_e64 v12, v152, v12
	v_mul_f32_e64 v13, v153, v13
	v_pk_mul_f32 v[14:15], v[154:155], v[14:15]
	v_cvt_pk_bf16_f32 v219, v10, v11
	v_cvt_pk_bf16_f32 v220, v12, v13
	v_cvt_pk_bf16_f32 v221, v14, v15
	global_load_dwordx4 v[172:175], v226, s[100:101] offset:384
	global_load_dwordx4 v[168:171], v227, s[100:101] offset:384
	s_waitcnt vmcnt(16)
	v_mfma_f32_32x32x16_bf16 v[16:31], v[76:79], v[210:213], v[16:31]
	global_load_dwordx4 v[164:167], v228, s[100:101] offset:384
	s_nop 0
	global_load_dwordx4 v[160:163], v229, s[100:101] offset:384
	v_mfma_f32_32x32x16_bf16 v[32:47], v[116:119], v[4:7], 0
	s_waitcnt vmcnt(17)
	v_mfma_f32_32x32x16_bf16 v[16:31], v[68:71], v[214:217], v[16:31]
	v_mfma_f32_32x32x16_bf16 v[48:63], v[120:123], v[4:7], 0
	v_mfma_f32_32x32x16_bf16 v[32:47], v[108:111], v[210:213], v[32:47]
	s_waitcnt vmcnt(15)
	v_mfma_f32_32x32x16_bf16 v[0:15], v[88:91], v[4:7], 0
	v_mfma_f32_32x32x16_bf16 v[16:31], v[64:67], v[218:221], v[16:31]
	v_mfma_f32_32x32x16_bf16 v[48:63], v[112:115], v[210:213], v[48:63]
	s_nop 10
	v_cvt_pk_bf16_f32 v16, v16, v17
	v_cvt_pk_bf16_f32 v17, v18, v19
	v_cvt_pk_bf16_f32 v18, v20, v21
	v_cvt_pk_bf16_f32 v19, v22, v23
	s_nop 0
	v_permlane32_swap_b32_e32 v16, v18
	v_permlane32_swap_b32_e32 v17, v19
	v_mfma_f32_32x32x16_bf16 v[32:47], v[100:103], v[214:217], v[32:47]
	global_store_dwordx4 v[208:209], v[16:19], off offset:128
	s_waitcnt vmcnt(12)
	v_lshlrev_b32_e32 v20, 16, v222
	v_and_b32_e32 v21, 0xffff0000, v222
	v_cvt_pk_bf16_f32 v16, v24, v25
	v_cvt_pk_bf16_f32 v17, v26, v27
	v_lshlrev_b32_e32 v22, 16, v223
	v_and_b32_e32 v23, 0xffff0000, v223
	v_mfma_f32_32x32x16_bf16 v[0:15], v[84:87], v[210:213], v[0:15]
	v_lshlrev_b32_e32 v24, 16, v224
	v_and_b32_e32 v25, 0xffff0000, v224
	v_lshlrev_b32_e32 v26, 16, v225
	v_and_b32_e32 v27, 0xffff0000, v225
	v_mul_f32_e64 v20, v148, v20
	v_mul_f32_e64 v21, v149, v21
	v_pk_mul_f32 v[22:23], v[150:151], v[22:23]
	v_pk_mul_f32 v[24:25], v[144:145], v[24:25]
	v_mfma_f32_32x32x16_bf16 v[48:63], v[104:107], v[214:217], v[48:63]
	v_mul_f32_e64 v26, v146, v26
	v_mul_f32_e64 v27, v147, v27
	v_cvt_pk_bf16_f32 v210, v20, v21
	v_cvt_pk_bf16_f32 v211, v22, v23
	v_cvt_pk_bf16_f32 v212, v24, v25
	v_cvt_pk_bf16_f32 v213, v26, v27
	s_waitcnt vmcnt(11)
	v_lshlrev_b32_e32 v20, 16, v200
	v_and_b32_e32 v21, 0xffff0000, v200
	v_lshlrev_b32_e32 v22, 16, v201
	v_and_b32_e32 v23, 0xffff0000, v201
	v_lshlrev_b32_e32 v24, 16, v202
	v_and_b32_e32 v25, 0xffff0000, v202
	v_lshlrev_b32_e32 v26, 16, v203
	v_and_b32_e32 v27, 0xffff0000, v203
	v_pk_mul_f32 v[20:21], v[128:129], v[20:21]
	v_pk_mul_f32 v[22:23], v[130:131], v[22:23]
	v_pk_mul_f32 v[24:25], v[132:133], v[24:25]
	v_pk_mul_f32 v[26:27], v[134:135], v[26:27]
	v_cvt_pk_bf16_f32 v200, v20, v21
	v_cvt_pk_bf16_f32 v201, v22, v23
	v_cvt_pk_bf16_f32 v202, v24, v25
	v_cvt_pk_bf16_f32 v203, v26, v27
	s_waitcnt vmcnt(10)
	v_lshlrev_b32_e32 v20, 16, v196
	v_and_b32_e32 v21, 0xffff0000, v196
	v_lshlrev_b32_e32 v22, 16, v197
	v_and_b32_e32 v23, 0xffff0000, v197
	v_lshlrev_b32_e32 v24, 16, v198
	v_and_b32_e32 v25, 0xffff0000, v198
	v_lshlrev_b32_e32 v26, 16, v199
	v_and_b32_e32 v27, 0xffff0000, v199
	v_pk_mul_f32 v[20:21], v[136:137], v[20:21]
	v_pk_mul_f32 v[22:23], v[138:139], v[22:23]
	v_pk_mul_f32 v[24:25], v[140:141], v[24:25]
	v_pk_mul_f32 v[26:27], v[142:143], v[26:27]
	v_mfma_f32_32x32x16_bf16 v[32:47], v[92:95], v[218:221], v[32:47]
	v_cvt_pk_bf16_f32 v18, v28, v29
	v_cvt_pk_bf16_f32 v196, v20, v21
	v_cvt_pk_bf16_f32 v197, v22, v23
	v_cvt_pk_bf16_f32 v198, v24, v25
	v_cvt_pk_bf16_f32 v199, v26, v27
	s_waitcnt vmcnt(9)
	v_lshlrev_b32_e32 v20, 16, v192
	v_and_b32_e32 v21, 0xffff0000, v192
	v_mfma_f32_32x32x16_bf16 v[0:15], v[72:75], v[214:217], v[0:15]
	v_lshlrev_b32_e32 v22, 16, v193
	v_and_b32_e32 v23, 0xffff0000, v193
	v_lshlrev_b32_e32 v24, 16, v194
	v_and_b32_e32 v25, 0xffff0000, v194
	v_lshlrev_b32_e32 v26, 16, v195
	v_and_b32_e32 v27, 0xffff0000, v195
	v_cvt_pk_bf16_f32 v19, v30, v31
	v_pk_mul_f32 v[20:21], v[156:157], v[20:21]
	v_pk_mul_f32 v[22:23], v[158:159], v[22:23]
	v_pk_mul_f32 v[24:25], v[152:153], v[24:25]
	v_pk_mul_f32 v[26:27], v[154:155], v[26:27]
	v_permlane32_swap_b32_e32 v16, v18
	v_permlane32_swap_b32_e32 v17, v19
	v_mfma_f32_32x32x16_bf16 v[48:63], v[96:99], v[218:221], v[48:63]
	v_cvt_pk_bf16_f32 v214, v20, v21
	v_cvt_pk_bf16_f32 v215, v22, v23
	v_cvt_pk_bf16_f32 v216, v24, v25
	v_cvt_pk_bf16_f32 v217, v26, v27
	global_store_dwordx4 v[208:209], v[16:19], off offset:160
	v_cvt_pk_bf16_f32 v32, v32, v33
	v_cvt_pk_bf16_f32 v33, v34, v35
	v_mfma_f32_32x32x16_bf16 v[16:31], v[80:83], v[210:213], 0
	v_cvt_pk_bf16_f32 v34, v36, v37
	v_cvt_pk_bf16_f32 v35, v38, v39
	s_nop 0
	v_permlane32_swap_b32_e32 v32, v34
	v_permlane32_swap_b32_e32 v33, v35
	v_cvt_pk_bf16_f32 v48, v48, v49
	v_mfma_f32_32x32x16_bf16 v[0:15], v[124:127], v[218:221], v[0:15]
	v_cvt_pk_bf16_f32 v49, v50, v51
	v_cvt_pk_bf16_f32 v50, v52, v53
	v_cvt_pk_bf16_f32 v51, v54, v55
	global_store_dwordx4 v[208:209], v[32:35], off offset:64
	v_permlane32_swap_b32_e32 v48, v50
	s_nop 0
	v_cvt_pk_bf16_f32 v32, v40, v41
	v_cvt_pk_bf16_f32 v33, v42, v43
	v_cvt_pk_bf16_f32 v34, v44, v45
	v_cvt_pk_bf16_f32 v35, v46, v47
	v_mfma_f32_32x32x16_bf16 v[16:31], v[76:79], v[200:203], v[16:31]
	v_permlane32_swap_b32_e32 v49, v51
	v_permlane32_swap_b32_e32 v32, v34
	v_permlane32_swap_b32_e32 v33, v35
	global_store_dwordx4 v[208:209], v[48:51], off
	global_store_dwordx4 v[208:209], v[32:35], off offset:96
	v_cvt_pk_bf16_f32 v0, v0, v1
	v_cvt_pk_bf16_f32 v48, v56, v57
	v_cvt_pk_bf16_f32 v49, v58, v59
	v_cvt_pk_bf16_f32 v50, v60, v61
	v_cvt_pk_bf16_f32 v51, v62, v63
	v_mfma_f32_32x32x16_bf16 v[32:47], v[116:119], v[210:213], 0
	v_permlane32_swap_b32_e32 v48, v50
	v_permlane32_swap_b32_e32 v49, v51
	global_store_dwordx4 v[208:209], v[48:51], off offset:32
	v_cvt_pk_bf16_f32 v1, v2, v3
	v_cvt_pk_bf16_f32 v2, v4, v5
	v_mfma_f32_32x32x16_bf16 v[48:63], v[120:123], v[210:213], 0
	v_cvt_pk_bf16_f32 v3, v6, v7
	v_permlane32_swap_b32_e32 v0, v2
	s_nop 0
	v_permlane32_swap_b32_e32 v1, v3
	global_store_dwordx4 v[208:209], v[0:3], off offset:192
	v_cvt_pk_bf16_f32 v192, v8, v9
	v_cvt_pk_bf16_f32 v193, v10, v11
	v_cvt_pk_bf16_f32 v194, v12, v13
	v_cvt_pk_bf16_f32 v195, v14, v15
	v_mfma_f32_32x32x16_bf16 v[0:15], v[88:91], v[210:213], 0
	v_permlane32_swap_b32_e32 v192, v194
	v_permlane32_swap_b32_e32 v193, v195
	global_store_dwordx4 v[208:209], v[192:195], off offset:224
	v_mfma_f32_32x32x16_bf16 v[16:31], v[68:71], v[196:199], v[16:31]
	s_nop 0
	v_add_co_u32_e32 v192, vcc, s94, v208
	s_nop 1
	v_addc_co_u32_e32 v193, vcc, 0, v209, vcc
	v_mfma_f32_32x32x16_bf16 v[32:47], v[108:111], v[200:203], v[32:47]
	v_mfma_f32_32x32x16_bf16 v[48:63], v[112:115], v[200:203], v[48:63]
	v_mfma_f32_32x32x16_bf16 v[0:15], v[84:87], v[200:203], v[0:15]
	v_mfma_f32_32x32x16_bf16 v[16:31], v[64:67], v[214:217], v[16:31]
	v_mfma_f32_32x32x16_bf16 v[32:47], v[100:103], v[196:199], v[32:47]
	s_nop 10
	v_cvt_pk_bf16_f32 v16, v16, v17
	v_cvt_pk_bf16_f32 v17, v18, v19
	v_cvt_pk_bf16_f32 v18, v20, v21
	v_cvt_pk_bf16_f32 v19, v22, v23
	s_nop 0
	v_permlane32_swap_b32_e32 v16, v18
	v_permlane32_swap_b32_e32 v17, v19
	v_mfma_f32_32x32x16_bf16 v[48:63], v[104:107], v[196:199], v[48:63]
	global_store_dwordx4 v[192:193], v[16:19], off offset:128
	s_waitcnt vmcnt(16)
	v_lshlrev_b32_e32 v20, 16, v188
	v_and_b32_e32 v21, 0xffff0000, v188
	v_cvt_pk_bf16_f32 v16, v24, v25
	v_cvt_pk_bf16_f32 v17, v26, v27
	v_lshlrev_b32_e32 v22, 16, v189
	v_and_b32_e32 v23, 0xffff0000, v189
	v_mfma_f32_32x32x16_bf16 v[0:15], v[72:75], v[196:199], v[0:15]
	v_lshlrev_b32_e32 v24, 16, v190
	v_and_b32_e32 v25, 0xffff0000, v190
	v_lshlrev_b32_e32 v26, 16, v191
	v_and_b32_e32 v27, 0xffff0000, v191
	v_mul_f32_e64 v20, v148, v20
	v_mul_f32_e64 v21, v149, v21
	v_pk_mul_f32 v[22:23], v[150:151], v[22:23]
	v_pk_mul_f32 v[24:25], v[144:145], v[24:25]
	v_mfma_f32_32x32x16_bf16 v[32:47], v[92:95], v[214:217], v[32:47]
	v_mul_f32_e64 v26, v146, v26
	v_mul_f32_e64 v27, v147, v27
	v_cvt_pk_bf16_f32 v188, v20, v21
	v_cvt_pk_bf16_f32 v189, v22, v23
	v_cvt_pk_bf16_f32 v190, v24, v25
	v_cvt_pk_bf16_f32 v191, v26, v27
	s_waitcnt vmcnt(15)
	v_lshlrev_b32_e32 v20, 16, v184
	v_and_b32_e32 v21, 0xffff0000, v184
	v_mfma_f32_32x32x16_bf16 v[48:63], v[96:99], v[214:217], v[48:63]
	v_lshlrev_b32_e32 v22, 16, v185
	v_and_b32_e32 v23, 0xffff0000, v185
	v_lshlrev_b32_e32 v24, 16, v186
	v_and_b32_e32 v25, 0xffff0000, v186
	v_lshlrev_b32_e32 v26, 16, v187
	v_and_b32_e32 v27, 0xffff0000, v187
	v_pk_mul_f32 v[20:21], v[128:129], v[20:21]
	v_pk_mul_f32 v[22:23], v[130:131], v[22:23]
	v_pk_mul_f32 v[24:25], v[132:133], v[24:25]
	v_pk_mul_f32 v[26:27], v[134:135], v[26:27]
	v_cvt_pk_bf16_f32 v184, v20, v21
	v_cvt_pk_bf16_f32 v185, v22, v23
	v_cvt_pk_bf16_f32 v186, v24, v25
	v_cvt_pk_bf16_f32 v187, v26, v27
	s_waitcnt vmcnt(14)
	v_lshlrev_b32_e32 v20, 16, v180
	v_and_b32_e32 v21, 0xffff0000, v180
	v_lshlrev_b32_e32 v22, 16, v181
	v_and_b32_e32 v23, 0xffff0000, v181
	v_lshlrev_b32_e32 v24, 16, v182
	v_and_b32_e32 v25, 0xffff0000, v182
	v_lshlrev_b32_e32 v26, 16, v183
	v_and_b32_e32 v27, 0xffff0000, v183
	v_pk_mul_f32 v[20:21], v[136:137], v[20:21]
	v_pk_mul_f32 v[22:23], v[138:139], v[22:23]
	v_pk_mul_f32 v[24:25], v[140:141], v[24:25]
	v_pk_mul_f32 v[26:27], v[142:143], v[26:27]
	v_mfma_f32_32x32x16_bf16 v[0:15], v[124:127], v[214:217], v[0:15]
	v_cvt_pk_bf16_f32 v18, v28, v29
	v_cvt_pk_bf16_f32 v180, v20, v21
	v_cvt_pk_bf16_f32 v181, v22, v23
	v_cvt_pk_bf16_f32 v182, v24, v25
	v_cvt_pk_bf16_f32 v183, v26, v27
	s_waitcnt vmcnt(13)
	v_lshlrev_b32_e32 v20, 16, v176
	v_and_b32_e32 v21, 0xffff0000, v176
	v_lshlrev_b32_e32 v22, 16, v177
	v_and_b32_e32 v23, 0xffff0000, v177
	v_lshlrev_b32_e32 v24, 16, v178
	v_and_b32_e32 v25, 0xffff0000, v178
	v_lshlrev_b32_e32 v26, 16, v179
	v_and_b32_e32 v27, 0xffff0000, v179
	v_cvt_pk_bf16_f32 v19, v30, v31
	v_pk_mul_f32 v[20:21], v[156:157], v[20:21]
	v_pk_mul_f32 v[22:23], v[158:159], v[22:23]
	v_pk_mul_f32 v[24:25], v[152:153], v[24:25]
	v_pk_mul_f32 v[26:27], v[154:155], v[26:27]
	v_permlane32_swap_b32_e32 v16, v18
	v_permlane32_swap_b32_e32 v17, v19
	v_cvt_pk_bf16_f32 v32, v32, v33
	v_cvt_pk_bf16_f32 v33, v34, v35
	v_cvt_pk_bf16_f32 v34, v36, v37
	v_cvt_pk_bf16_f32 v35, v38, v39
	v_cvt_pk_bf16_f32 v194, v20, v21
	v_cvt_pk_bf16_f32 v195, v22, v23
	v_cvt_pk_bf16_f32 v196, v24, v25
	v_cvt_pk_bf16_f32 v197, v26, v27
	global_store_dwordx4 v[192:193], v[16:19], off offset:160
	v_permlane32_swap_b32_e32 v32, v34
	s_nop 0
	v_mfma_f32_32x32x16_bf16 v[16:31], v[80:83], v[188:191], 0
	v_permlane32_swap_b32_e32 v33, v35
	v_cvt_pk_bf16_f32 v48, v48, v49
	v_cvt_pk_bf16_f32 v49, v50, v51
	v_cvt_pk_bf16_f32 v50, v52, v53
	v_cvt_pk_bf16_f32 v51, v54, v55
	global_store_dwordx4 v[192:193], v[32:35], off offset:64
	v_permlane32_swap_b32_e32 v48, v50
	s_nop 0
	v_cvt_pk_bf16_f32 v32, v40, v41
	v_cvt_pk_bf16_f32 v33, v42, v43
	v_cvt_pk_bf16_f32 v34, v44, v45
	v_cvt_pk_bf16_f32 v35, v46, v47
	v_permlane32_swap_b32_e32 v49, v51
	v_permlane32_swap_b32_e32 v32, v34
	v_permlane32_swap_b32_e32 v33, v35
	global_store_dwordx4 v[192:193], v[48:51], off
	global_store_dwordx4 v[192:193], v[32:35], off offset:96
	v_cvt_pk_bf16_f32 v0, v0, v1
	v_cvt_pk_bf16_f32 v48, v56, v57
	v_cvt_pk_bf16_f32 v49, v58, v59
	v_cvt_pk_bf16_f32 v50, v60, v61
	v_cvt_pk_bf16_f32 v51, v62, v63
	v_mfma_f32_32x32x16_bf16 v[32:47], v[116:119], v[188:191], 0
	v_permlane32_swap_b32_e32 v48, v50
	v_permlane32_swap_b32_e32 v49, v51
	global_store_dwordx4 v[192:193], v[48:51], off offset:32
	v_cvt_pk_bf16_f32 v1, v2, v3
	v_cvt_pk_bf16_f32 v2, v4, v5
	v_mfma_f32_32x32x16_bf16 v[48:63], v[120:123], v[188:191], 0
	v_cvt_pk_bf16_f32 v3, v6, v7
	v_permlane32_swap_b32_e32 v0, v2
	s_nop 0
	v_permlane32_swap_b32_e32 v1, v3
	global_store_dwordx4 v[192:193], v[0:3], off offset:192
	v_cvt_pk_bf16_f32 v176, v8, v9
	v_cvt_pk_bf16_f32 v177, v10, v11
	v_cvt_pk_bf16_f32 v178, v12, v13
	v_cvt_pk_bf16_f32 v179, v14, v15
	v_mfma_f32_32x32x16_bf16 v[0:15], v[88:91], v[188:191], 0
	v_permlane32_swap_b32_e32 v176, v178
	v_permlane32_swap_b32_e32 v177, v179
	global_store_dwordx4 v[192:193], v[176:179], off offset:224
	v_mfma_f32_32x32x16_bf16 v[16:31], v[76:79], v[184:187], v[16:31]
	s_nop 0
	v_add_co_u32_e32 v176, vcc, s95, v208
	s_nop 1
	v_addc_co_u32_e32 v177, vcc, 0, v209, vcc
	v_mfma_f32_32x32x16_bf16 v[32:47], v[108:111], v[184:187], v[32:47]
	v_mfma_f32_32x32x16_bf16 v[48:63], v[112:115], v[184:187], v[48:63]
	v_mfma_f32_32x32x16_bf16 v[0:15], v[84:87], v[184:187], v[0:15]
	v_mfma_f32_32x32x16_bf16 v[16:31], v[68:71], v[180:183], v[16:31]
	v_mfma_f32_32x32x16_bf16 v[32:47], v[100:103], v[180:183], v[32:47]
	v_mfma_f32_32x32x16_bf16 v[48:63], v[104:107], v[180:183], v[48:63]
	v_mfma_f32_32x32x16_bf16 v[0:15], v[72:75], v[180:183], v[0:15]
	v_mfma_f32_32x32x16_bf16 v[16:31], v[64:67], v[194:197], v[16:31]
	v_mfma_f32_32x32x16_bf16 v[32:47], v[92:95], v[194:197], v[32:47]
	s_nop 10
	v_cvt_pk_bf16_f32 v16, v16, v17
	v_cvt_pk_bf16_f32 v17, v18, v19
	v_cvt_pk_bf16_f32 v18, v20, v21
	v_cvt_pk_bf16_f32 v19, v22, v23
	s_nop 0
	v_permlane32_swap_b32_e32 v16, v18
	v_permlane32_swap_b32_e32 v17, v19
	v_mfma_f32_32x32x16_bf16 v[48:63], v[96:99], v[194:197], v[48:63]
	global_store_dwordx4 v[176:177], v[16:19], off offset:128
	s_waitcnt vmcnt(20)
	v_lshlrev_b32_e32 v20, 16, v172
	v_and_b32_e32 v21, 0xffff0000, v172
	v_cvt_pk_bf16_f32 v16, v24, v25
	v_cvt_pk_bf16_f32 v17, v26, v27
	v_lshlrev_b32_e32 v22, 16, v173
	v_and_b32_e32 v23, 0xffff0000, v173
	v_mfma_f32_32x32x16_bf16 v[0:15], v[124:127], v[194:197], v[0:15]
	v_lshlrev_b32_e32 v24, 16, v174
	v_and_b32_e32 v25, 0xffff0000, v174
	v_lshlrev_b32_e32 v26, 16, v175
	v_and_b32_e32 v27, 0xffff0000, v175
	v_mul_f32_e64 v20, v148, v20
	v_mul_f32_e64 v21, v149, v21
	v_pk_mul_f32 v[22:23], v[150:151], v[22:23]
	v_pk_mul_f32 v[24:25], v[144:145], v[24:25]
	v_pk_mul_f32 v[26:27], v[146:147], v[26:27]
	v_cvt_pk_bf16_f32 v32, v32, v33
	v_cvt_pk_bf16_f32 v33, v34, v35
	v_cvt_pk_bf16_f32 v34, v36, v37
	v_cvt_pk_bf16_f32 v35, v38, v39
	v_cvt_pk_bf16_f32 v172, v20, v21
	v_cvt_pk_bf16_f32 v173, v22, v23
	v_cvt_pk_bf16_f32 v174, v24, v25
	v_cvt_pk_bf16_f32 v175, v26, v27
	s_waitcnt vmcnt(19)
	v_lshlrev_b32_e32 v20, 16, v168
	v_and_b32_e32 v21, 0xffff0000, v168
	v_lshlrev_b32_e32 v22, 16, v169
	v_and_b32_e32 v23, 0xffff0000, v169
	v_lshlrev_b32_e32 v24, 16, v170
	v_and_b32_e32 v25, 0xffff0000, v170
	v_lshlrev_b32_e32 v26, 16, v171
	v_and_b32_e32 v27, 0xffff0000, v171
	v_permlane32_swap_b32_e32 v32, v34
	v_permlane32_swap_b32_e32 v33, v35
	v_pk_mul_f32 v[20:21], v[128:129], v[20:21]
	v_pk_mul_f32 v[22:23], v[130:131], v[22:23]
	v_pk_mul_f32 v[24:25], v[132:133], v[24:25]
	v_pk_mul_f32 v[26:27], v[134:135], v[26:27]
	v_cvt_pk_bf16_f32 v48, v48, v49
	v_cvt_pk_bf16_f32 v49, v50, v51
	v_cvt_pk_bf16_f32 v50, v52, v53
	v_cvt_pk_bf16_f32 v51, v54, v55
	global_store_dwordx4 v[176:177], v[32:35], off offset:64
	v_cvt_pk_bf16_f32 v168, v20, v21
	v_cvt_pk_bf16_f32 v169, v22, v23
	v_cvt_pk_bf16_f32 v32, v40, v41
	v_cvt_pk_bf16_f32 v33, v42, v43
	v_cvt_pk_bf16_f32 v34, v44, v45
	v_cvt_pk_bf16_f32 v35, v46, v47
	v_cvt_pk_bf16_f32 v170, v24, v25
	v_cvt_pk_bf16_f32 v171, v26, v27
	s_waitcnt vmcnt(19)
	v_lshlrev_b32_e32 v20, 16, v164
	v_and_b32_e32 v21, 0xffff0000, v164
	v_lshlrev_b32_e32 v22, 16, v165
	v_and_b32_e32 v23, 0xffff0000, v165
	v_lshlrev_b32_e32 v24, 16, v166
	v_and_b32_e32 v25, 0xffff0000, v166
	v_lshlrev_b32_e32 v26, 16, v167
	v_and_b32_e32 v27, 0xffff0000, v167
	v_permlane32_swap_b32_e32 v48, v50
	v_permlane32_swap_b32_e32 v49, v51
	v_permlane32_swap_b32_e32 v32, v34
	v_permlane32_swap_b32_e32 v33, v35
	v_pk_mul_f32 v[20:21], v[136:137], v[20:21]
	v_pk_mul_f32 v[22:23], v[138:139], v[22:23]
	v_pk_mul_f32 v[24:25], v[140:141], v[24:25]
	v_pk_mul_f32 v[26:27], v[142:143], v[26:27]
	global_store_dwordx4 v[176:177], v[48:51], off
	global_store_dwordx4 v[176:177], v[32:35], off offset:96
	v_cvt_pk_bf16_f32 v18, v28, v29
	v_cvt_pk_bf16_f32 v48, v56, v57
	v_cvt_pk_bf16_f32 v49, v58, v59
	v_cvt_pk_bf16_f32 v50, v60, v61
	v_cvt_pk_bf16_f32 v51, v62, v63
	v_mfma_f32_32x32x16_bf16 v[32:47], v[116:119], v[172:175], 0
	v_cvt_pk_bf16_f32 v164, v20, v21
	v_cvt_pk_bf16_f32 v165, v22, v23
	v_cvt_pk_bf16_f32 v166, v24, v25
	v_cvt_pk_bf16_f32 v167, v26, v27
	s_waitcnt vmcnt(20)
	v_lshlrev_b32_e32 v20, 16, v160
	v_and_b32_e32 v21, 0xffff0000, v160
	v_lshlrev_b32_e32 v22, 16, v161
	v_and_b32_e32 v23, 0xffff0000, v161
	v_lshlrev_b32_e32 v24, 16, v162
	v_and_b32_e32 v25, 0xffff0000, v162
	v_lshlrev_b32_e32 v26, 16, v163
	v_and_b32_e32 v27, 0xffff0000, v163
	v_cvt_pk_bf16_f32 v19, v30, v31
	v_cvt_pk_bf16_f32 v0, v0, v1
	v_cvt_pk_bf16_f32 v1, v2, v3
	v_cvt_pk_bf16_f32 v2, v4, v5
	v_cvt_pk_bf16_f32 v3, v6, v7
	v_permlane32_swap_b32_e32 v48, v50
	v_permlane32_swap_b32_e32 v49, v51
	v_pk_mul_f32 v[20:21], v[156:157], v[20:21]
	v_pk_mul_f32 v[22:23], v[158:159], v[22:23]
	v_pk_mul_f32 v[24:25], v[152:153], v[24:25]
	v_pk_mul_f32 v[26:27], v[154:155], v[26:27]
	v_permlane32_swap_b32_e32 v16, v18
	v_permlane32_swap_b32_e32 v17, v19
	v_permlane32_swap_b32_e32 v0, v2
	v_permlane32_swap_b32_e32 v1, v3
	global_store_dwordx4 v[176:177], v[48:51], off offset:32
	v_cvt_pk_bf16_f32 v160, v20, v21
	v_cvt_pk_bf16_f32 v161, v22, v23
	v_mfma_f32_32x32x16_bf16 v[48:63], v[120:123], v[172:175], 0
	v_cvt_pk_bf16_f32 v162, v24, v25
	v_cvt_pk_bf16_f32 v163, v26, v27
	global_store_dwordx4 v[176:177], v[16:19], off offset:160
	global_store_dwordx4 v[176:177], v[0:3], off offset:192
	v_cvt_pk_bf16_f32 v178, v8, v9
	v_cvt_pk_bf16_f32 v179, v10, v11
	v_cvt_pk_bf16_f32 v180, v12, v13
	v_mfma_f32_32x32x16_bf16 v[16:31], v[80:83], v[172:175], 0
	v_cvt_pk_bf16_f32 v181, v14, v15
	v_permlane32_swap_b32_e32 v178, v180
	s_nop 0
	v_permlane32_swap_b32_e32 v179, v181
	global_store_dwordx4 v[176:177], v[178:181], off offset:224
	v_mfma_f32_32x32x16_bf16 v[0:15], v[88:91], v[172:175], 0
	v_add_co_u32_e32 v172, vcc, s0, v208
	s_nop 1
	v_addc_co_u32_e32 v173, vcc, 0, v209, vcc
	v_mfma_f32_32x32x16_bf16 v[32:47], v[108:111], v[168:171], v[32:47]
	v_mfma_f32_32x32x16_bf16 v[48:63], v[112:115], v[168:171], v[48:63]
	v_mfma_f32_32x32x16_bf16 v[16:31], v[76:79], v[168:171], v[16:31]
	v_mfma_f32_32x32x16_bf16 v[0:15], v[84:87], v[168:171], v[0:15]
	v_mfma_f32_32x32x16_bf16 v[32:47], v[100:103], v[164:167], v[32:47]
	v_mfma_f32_32x32x16_bf16 v[48:63], v[104:107], v[164:167], v[48:63]
	v_mfma_f32_32x32x16_bf16 v[16:31], v[68:71], v[164:167], v[16:31]
	v_mfma_f32_32x32x16_bf16 v[0:15], v[72:75], v[164:167], v[0:15]
	v_mfma_f32_32x32x16_bf16 v[32:47], v[92:95], v[160:163], v[32:47]
	v_mfma_f32_32x32x16_bf16 v[48:63], v[96:99], v[160:163], v[48:63]
	s_nop 10
	v_cvt_pk_bf16_f32 v32, v32, v33
	v_cvt_pk_bf16_f32 v33, v34, v35
	v_cvt_pk_bf16_f32 v34, v36, v37
	v_cvt_pk_bf16_f32 v35, v38, v39
	s_nop 0
	v_permlane32_swap_b32_e32 v32, v34
	v_permlane32_swap_b32_e32 v33, v35
	v_mfma_f32_32x32x16_bf16 v[16:31], v[64:67], v[160:163], v[16:31]
	v_cvt_pk_bf16_f32 v48, v48, v49
	v_cvt_pk_bf16_f32 v49, v50, v51
	v_cvt_pk_bf16_f32 v50, v52, v53
	v_cvt_pk_bf16_f32 v51, v54, v55
	global_store_dwordx4 v[172:173], v[32:35], off offset:64
	v_permlane32_swap_b32_e32 v48, v50
	v_mfma_f32_32x32x16_bf16 v[0:15], v[124:127], v[160:163], v[0:15]
	v_cvt_pk_bf16_f32 v32, v40, v41
	v_cvt_pk_bf16_f32 v33, v42, v43
	v_cvt_pk_bf16_f32 v34, v44, v45
	v_cvt_pk_bf16_f32 v35, v46, v47
	s_nop 0
	v_cvt_pk_bf16_f32 v16, v16, v17
	v_cvt_pk_bf16_f32 v17, v18, v19
	v_cvt_pk_bf16_f32 v18, v20, v21
	v_cvt_pk_bf16_f32 v19, v22, v23
	s_nop 2
	v_cvt_pk_bf16_f32 v52, v0, v1
	v_cvt_pk_bf16_f32 v53, v2, v3
	v_cvt_pk_bf16_f32 v54, v4, v5
	v_cvt_pk_bf16_f32 v55, v6, v7
	v_cndmask_b32_e64 v0, 0, v148, s[4:5]
	v_cndmask_b32_e64 v1, 0, v149, s[4:5]
	v_cndmask_b32_e64 v2, 0, v150, s[4:5]
	v_cndmask_b32_e64 v3, 0, v151, s[4:5]
	v_cndmask_b32_e64 v4, 0, v144, s[4:5]
	v_cndmask_b32_e64 v5, 0, v145, s[4:5]
	v_cndmask_b32_e64 v6, 0, v146, s[4:5]
	v_cndmask_b32_e64 v7, 0, v147, s[4:5]
	v_permlane32_swap_b32_e32 v32, v34
	v_permlane32_swap_b32_e32 v33, v35
	v_permlane32_swap_b32_e32 v16, v18
	v_permlane32_swap_b32_e32 v17, v19
	v_cvt_pk_bf16_f32 v0, v0, v1
	v_cvt_pk_bf16_f32 v1, v2, v3
	v_cvt_pk_bf16_f32 v2, v4, v5
	v_cvt_pk_bf16_f32 v3, v6, v7
	global_store_dwordx4 v[172:173], v[32:35], off offset:96
	global_store_dwordx4 v[172:173], v[16:19], off offset:128
	v_permlane32_swap_b32_e32 v49, v51
	s_nop 0
	v_cvt_pk_bf16_f32 v16, v24, v25
	v_cvt_pk_bf16_f32 v17, v26, v27
	v_cvt_pk_bf16_f32 v18, v28, v29
	v_cvt_pk_bf16_f32 v19, v30, v31
	v_mfma_f32_32x32x16_bf16 v[32:47], v[120:123], v[0:3], 0
	v_permlane32_swap_b32_e32 v16, v18
	v_permlane32_swap_b32_e32 v17, v19
	global_store_dwordx4 v[172:173], v[16:19], off offset:160
	global_store_dwordx4 v[172:173], v[48:51], off
	v_cndmask_b32_e64 v4, 0, v128, s[4:5]
	v_mfma_f32_32x32x16_bf16 v[16:31], v[116:119], v[0:3], 0
	v_cvt_pk_bf16_f32 v48, v56, v57
	v_cvt_pk_bf16_f32 v49, v58, v59
	v_cvt_pk_bf16_f32 v50, v60, v61
	v_cvt_pk_bf16_f32 v51, v62, v63
	s_nop 0
	v_permlane32_swap_b32_e32 v48, v50
	v_permlane32_swap_b32_e32 v49, v51
	global_store_dwordx4 v[172:173], v[48:51], off offset:32
	v_cndmask_b32_e64 v5, 0, v129, s[4:5]
	v_cndmask_b32_e64 v6, 0, v130, s[4:5]
	v_cndmask_b32_e64 v7, 0, v131, s[4:5]
	v_cndmask_b32_e64 v50, 0, v132, s[4:5]
	v_cndmask_b32_e64 v51, 0, v133, s[4:5]
	v_cndmask_b32_e64 v56, 0, v134, s[4:5]
	v_cndmask_b32_e64 v57, 0, v135, s[4:5]
	v_cvt_pk_bf16_f32 v48, v4, v5
	v_cvt_pk_bf16_f32 v49, v6, v7
	v_cvt_pk_bf16_f32 v50, v50, v51
	v_cvt_pk_bf16_f32 v51, v56, v57
	v_permlane32_swap_b32_e32 v52, v54
	s_nop 0
	v_mfma_f32_32x32x16_bf16 v[32:47], v[112:115], v[48:51], v[32:47]
	v_permlane32_swap_b32_e32 v53, v55
	global_store_dwordx4 v[172:173], v[52:55], off offset:192
	v_cndmask_b32_e64 v4, 0, v136, s[4:5]
	v_cndmask_b32_e64 v5, 0, v137, s[4:5]
	v_cndmask_b32_e64 v6, 0, v138, s[4:5]
	v_cndmask_b32_e64 v7, 0, v139, s[4:5]
	v_mfma_f32_32x32x16_bf16 v[16:31], v[108:111], v[48:51], v[16:31]
	v_cndmask_b32_e64 v54, 0, v140, s[4:5]
	v_cndmask_b32_e64 v55, 0, v141, s[4:5]
	v_cndmask_b32_e64 v56, 0, v142, s[4:5]
	v_cndmask_b32_e64 v57, 0, v143, s[4:5]
	v_cvt_pk_bf16_f32 v52, v4, v5
	v_cvt_pk_bf16_f32 v53, v6, v7
	v_cvt_pk_bf16_f32 v54, v54, v55
	v_cvt_pk_bf16_f32 v55, v56, v57
	v_cvt_pk_bf16_f32 v4, v8, v9
	v_cvt_pk_bf16_f32 v5, v10, v11
	v_mfma_f32_32x32x16_bf16 v[32:47], v[104:107], v[52:55], v[32:47]
	v_cndmask_b32_e64 v6, 0, v156, s[4:5]
	v_cndmask_b32_e64 v7, 0, v157, s[4:5]
	v_cndmask_b32_e64 v8, 0, v158, s[4:5]
	v_cndmask_b32_e64 v9, 0, v159, s[4:5]
	v_cndmask_b32_e64 v10, 0, v152, s[4:5]
	v_cndmask_b32_e64 v11, 0, v153, s[4:5]
	v_cndmask_b32_e64 v59, 0, v154, s[4:5]
	v_mfma_f32_32x32x16_bf16 v[16:31], v[100:103], v[52:55], v[16:31]
	v_cndmask_b32_e64 v60, 0, v155, s[4:5]
	v_cvt_pk_bf16_f32 v56, v6, v7
	v_cvt_pk_bf16_f32 v57, v8, v9
	v_cvt_pk_bf16_f32 v58, v10, v11
	v_cvt_pk_bf16_f32 v59, v59, v60
	v_cvt_pk_bf16_f32 v6, v12, v13
	v_cvt_pk_bf16_f32 v7, v14, v15
	v_mfma_f32_32x32x16_bf16 v[32:47], v[96:99], v[56:59], v[32:47]
	v_permlane32_swap_b32_e32 v4, v6
	v_permlane32_swap_b32_e32 v5, v7
	global_store_dwordx4 v[172:173], v[4:7], off offset:224
	v_mfma_f32_32x32x16_bf16 v[16:31], v[92:95], v[56:59], v[16:31]
	s_nop 7
	v_cvt_pk_bf16_f32 v4, v32, v33
	v_cvt_pk_bf16_f32 v5, v34, v35
	v_cvt_pk_bf16_f32 v6, v36, v37
	v_cvt_pk_bf16_f32 v7, v38, v39
	s_nop 0
	v_permlane32_swap_b32_e32 v4, v6
	v_permlane32_swap_b32_e32 v5, v7
	s_and_saveexec_b64 s[66:67], s[4:5]
	s_cbranch_execz .LBB0_414
	v_add_co_u32_e32 v8, vcc, 0x8000, v208
	s_nop 1
	v_addc_co_u32_e32 v9, vcc, 0, v209, vcc
	global_store_dwordx4 v[8:9], v[4:7], off

.LBB0_695:
	s_or_b64 exec, exec, s[4:5]
	s_waitcnt lgkmcnt(0)
	v_mov_b32_e32 v0, v207
	s_barrier
	s_nop 0
	v_ashrrev_i32_e32 v0, 6, v0
	v_lshl_add_u32 v0, s76, 2, v0
	s_nop 0
	v_readfirstlane_b32 s2, v0
	s_cmpk_gt_i32 s2, 0x7ff
	s_cbranch_scc1 .LBB0_724
	s_lshl_b32 s0, s2, 5
	s_lshl_b32 s28, s42, 2
	s_and_b32 s29, s0, 32
	s_add_u32 s4, s58, 0x9cd1000
	s_addc_u32 s5, s59, 0
	s_add_u32 s30, s58, 0xc50000
	s_addc_u32 s31, s59, 0
	s_add_u32 s33, s58, 0xdcd1000
	s_addc_u32 s34, s59, 0
	s_add_u32 s6, s58, 0xccd1000
	v_mbcnt_lo_u32_b32 v0, -1, 0
	s_addc_u32 s7, s59, 0
	s_add_i32 s35, s29, 32
	s_mov_b32 s9, 0
	v_mov_b32_e32 v133, 0
	s_mov_b64 s[10:11], 0x8000
	s_movk_i32 s36, 0x2000
	s_movk_i32 s37, 0x4000
	s_movk_i32 s40, 0x6000
	s_mov_b64 s[12:13], 0xacd1080
	s_mov_b32 s41, 0xbcd1000
	s_mov_b32 s52, 0xbcd2000
	s_mov_b32 s53, 0xbcd3000
	s_mov_b32 s62, 0xbcd4000
	s_add_u32 s98, s58, 0xbcd1000
	s_addc_u32 s99, s59, 0
	s_mov_b64 s[14:15], 0x80
	s_movk_i32 s63, 0x1800
	s_mov_b64 s[16:17], 0x2cd2400
	s_mov_b32 s66, 0x2cd2000
	s_mov_b64 s[18:19], 0xcd1400
	v_mov_b32_e32 v141, 0x3727c5ac
	s_mov_b32 s67, 0x800000
	s_mov_b32 s68, 0xcd1000
	v_mbcnt_hi_u32_b32 v143, -1, v0
	s_branch .LBB0_698

.LBB0_714:
	s_or_b64 exec, exec, s[26:27]
	v_lshlrev_b32_e32 v153, 3, v144
	v_lshlrev_b32_e32 v134, 1, v153
	v_mov_b32_e32 v135, v133
	v_lshl_add_u64 v[16:17], s[24:25], 0, v[134:135]
	v_lshlrev_b32_e32 v18, 8, v132
	v_mov_b32_e32 v19, v133
	v_lshl_add_u64 v[84:85], v[16:17], 0, v[18:19]
	v_add_co_u32_e32 v80, vcc, s36, v84
	global_load_dwordx4 v[16:19], v[84:85], off
	s_nop 0
	v_addc_co_u32_e32 v81, vcc, 0, v85, vcc
	global_load_dwordx4 v[20:23], v[80:81], off
	v_add_co_u32_e32 v82, vcc, s37, v84
	s_lshr_b32 s0, s2, 1
	s_nop 0
	v_addc_co_u32_e32 v83, vcc, 0, v85, vcc
	global_load_dwordx4 v[24:27], v[82:83], off
	global_load_dwordx4 v[64:67], v[84:85], off offset:32
	global_load_dwordx4 v[68:71], v[80:81], off offset:32
	global_load_dwordx4 v[76:79], v[84:85], off offset:64
	global_load_dwordx4 v[72:75], v[82:83], off offset:32
	v_add_co_u32_e32 v162, vcc, s40, v84
	s_and_b32 s24, s0, 63
	s_nop 0
	v_addc_co_u32_e32 v163, vcc, 0, v85, vcc
	s_lshl_b32 s1, s2, 1
	s_lshl_b32 s0, s24, 6
	s_and_b32 s25, s1, 0x300
	s_lshl_b32 s26, s24, 8
	s_add_u32 s0, s22, s0
	s_addc_u32 s1, s23, 0
	s_waitcnt vmcnt(7)
	v_mfma_f32_32x32x16_bf16 v[0:15], v[128:131], v[124:127], v[0:15]
	v_lshlrev_b32_e32 v144, 2, v144
	v_mov_b32_e32 v135, v140
	s_waitcnt vmcnt(6)
	v_mfma_f32_32x32x16_bf16 v[48:63], v[16:19], v[96:99], 0
	s_waitcnt vmcnt(5)
	v_mfma_f32_32x32x16_bf16 v[32:47], v[20:23], v[96:99], 0
	s_waitcnt vmcnt(3)
	v_mfma_f32_32x32x16_bf16 v[48:63], v[64:67], v[100:103], v[48:63]
	global_load_dwordx4 v[64:67], v[80:81], off offset:64
	s_waitcnt vmcnt(3)
	v_mfma_f32_32x32x16_bf16 v[32:47], v[68:71], v[100:103], v[32:47]
	global_load_dwordx4 v[68:71], v[84:85], off offset:96
	s_waitcnt vmcnt(3)
	v_mfma_f32_32x32x16_bf16 v[48:63], v[76:79], v[104:107], v[48:63]
	global_load_dwordx4 v[76:79], v[84:85], off offset:128
	v_mfma_f32_32x32x16_bf16 v[16:31], v[24:27], v[96:99], 0
	s_waitcnt vmcnt(2)
	v_mfma_f32_32x32x16_bf16 v[32:47], v[64:67], v[104:107], v[32:47]
	global_load_dwordx4 v[64:67], v[80:81], off offset:128
	s_waitcnt vmcnt(2)
	v_mfma_f32_32x32x16_bf16 v[48:63], v[68:71], v[108:111], v[48:63]
	global_load_dwordx4 v[68:71], v[84:85], off offset:160
	s_waitcnt vmcnt(2)
	v_mfma_f32_32x32x16_bf16 v[48:63], v[76:79], v[112:115], v[48:63]
	global_load_dwordx4 v[76:79], v[84:85], off offset:192
	s_waitcnt vmcnt(1)
	v_mfma_f32_32x32x16_bf16 v[48:63], v[68:71], v[116:119], v[48:63]
	global_load_dwordx4 v[68:71], v[84:85], off offset:224
	s_waitcnt vmcnt(1)
	v_mfma_f32_32x32x16_bf16 v[48:63], v[76:79], v[120:123], v[48:63]
	global_load_dwordx4 v[76:79], v[82:83], off offset:64
	s_waitcnt vmcnt(1)
	v_mfma_f32_32x32x16_bf16 v[48:63], v[68:71], v[124:127], v[48:63]
	global_load_dwordx4 v[68:71], v[82:83], off offset:128
	v_mfma_f32_32x32x16_bf16 v[16:31], v[72:75], v[100:103], v[16:31]
	global_load_dwordx4 v[72:75], v[80:81], off offset:96
	s_waitcnt vmcnt(0)
	v_mfma_f32_32x32x16_bf16 v[32:47], v[72:75], v[108:111], v[32:47]
	global_load_dwordx4 v[72:75], v[80:81], off offset:160
	v_mfma_f32_32x32x16_bf16 v[32:47], v[64:67], v[112:115], v[32:47]
	global_load_dwordx4 v[64:67], v[80:81], off offset:192
	s_waitcnt vmcnt(1)
	v_mfma_f32_32x32x16_bf16 v[32:47], v[72:75], v[116:119], v[32:47]
	global_load_dwordx4 v[72:75], v[80:81], off offset:224
	s_waitcnt vmcnt(1)
	v_mfma_f32_32x32x16_bf16 v[32:47], v[64:67], v[120:123], v[32:47]
	global_load_dwordx4 v[64:67], v[82:83], off offset:96
	s_waitcnt vmcnt(1)
	v_mfma_f32_32x32x16_bf16 v[32:47], v[72:75], v[124:127], v[32:47]
	global_load_dwordx4 v[72:75], v[82:83], off offset:160
	v_mfma_f32_32x32x16_bf16 v[16:31], v[76:79], v[104:107], v[16:31]
	global_load_dwordx4 v[76:79], v[82:83], off offset:192
	s_nop 0
	global_load_dwordx4 v[80:83], v[82:83], off offset:224
	s_nop 0
	global_load_dwordx4 v[148:151], v[162:163], off offset:128
	global_load_dwordx4 v[154:157], v[162:163], off offset:160
	global_load_dwordx4 v[158:161], v[162:163], off offset:192
	s_waitcnt vmcnt(6)
	v_mfma_f32_32x32x16_bf16 v[16:31], v[64:67], v[108:111], v[16:31]
	global_load_dwordx4 v[64:67], v[162:163], off
	v_mfma_f32_32x32x16_bf16 v[16:31], v[68:71], v[112:115], v[16:31]
	global_load_dwordx4 v[68:71], v[162:163], off offset:32
	s_waitcnt vmcnt(7)
	v_mfma_f32_32x32x16_bf16 v[16:31], v[72:75], v[116:119], v[16:31]
	global_load_dwordx4 v[72:75], v[162:163], off offset:64
	s_waitcnt vmcnt(7)
	v_mfma_f32_32x32x16_bf16 v[16:31], v[76:79], v[120:123], v[16:31]
	global_load_dwordx4 v[76:79], v[162:163], off offset:96
	s_nop 0
	global_load_dwordx4 v[162:165], v[162:163], off offset:224
	s_waitcnt vmcnt(8)
	v_mfma_f32_32x32x16_bf16 v[16:31], v[80:83], v[124:127], v[16:31]
	s_waitcnt vmcnt(4)
	v_mfma_f32_32x32x16_bf16 v[80:95], v[64:67], v[96:99], 0
	v_mul_f32_e32 v64, 0x3fb8aa3b, v152
	v_exp_f32_e32 v142, v64
	s_nop 0
	v_pk_mul_f32 v[66:67], v[142:143], v[50:51] op_sel_hi:[0,1]
	v_pk_mul_f32 v[64:65], v[142:143], v[48:49] op_sel_hi:[0,1]
	s_waitcnt vmcnt(3)
	v_mfma_f32_32x32x16_bf16 v[80:95], v[68:71], v[100:103], v[80:95]
	v_mul_f32_e64 v50, v142, v34
	v_mul_f32_e64 v51, v142, v35
	v_mul_f32_e64 v48, v142, v32
	v_mul_f32_e64 v49, v142, v33
	v_mul_f32_e64 v34, v142, v18
	v_mul_f32_e64 v35, v142, v19
	v_pk_mul_f32 v[32:33], v[142:143], v[16:17] op_sel_hi:[0,1]
	v_pk_mul_f32 v[70:71], v[142:143], v[54:55] op_sel_hi:[0,1]
	v_pk_mul_f32 v[68:69], v[142:143], v[52:53] op_sel_hi:[0,1]
	v_pk_mul_f32 v[54:55], v[142:143], v[38:39] op_sel_hi:[0,1]
	v_pk_mul_f32 v[52:53], v[142:143], v[36:37] op_sel_hi:[0,1]
	v_pk_mul_f32 v[38:39], v[142:143], v[22:23] op_sel_hi:[0,1]
	v_pk_mul_f32 v[36:37], v[142:143], v[20:21] op_sel_hi:[0,1]
	s_waitcnt vmcnt(2)
	v_mfma_f32_32x32x16_bf16 v[80:95], v[72:75], v[104:107], v[80:95]
	v_mul_f32_e64 v74, v142, v58
	v_mul_f32_e64 v75, v142, v59
	v_mul_f32_e64 v72, v142, v56
	v_mul_f32_e64 v73, v142, v57
	v_mul_f32_e64 v58, v142, v42
	v_mul_f32_e64 v59, v142, v43
	v_pk_mul_f32 v[56:57], v[142:143], v[40:41] op_sel_hi:[0,1]
	v_pk_mul_f32 v[42:43], v[142:143], v[26:27] op_sel_hi:[0,1]
	v_pk_mul_f32 v[40:41], v[142:143], v[24:25] op_sel_hi:[0,1]
	s_waitcnt vmcnt(1)
	v_mfma_f32_32x32x16_bf16 v[80:95], v[76:79], v[108:111], v[80:95]
	v_mul_f32_e64 v78, v142, v62
	v_mul_f32_e64 v79, v142, v63
	v_mul_f32_e64 v76, v142, v60
	v_mul_f32_e64 v77, v142, v61
	v_mul_f32_e64 v62, v142, v46
	v_mul_f32_e64 v63, v142, v47
	v_pk_mul_f32 v[60:61], v[142:143], v[44:45] op_sel_hi:[0,1]
	v_pk_mul_f32 v[46:47], v[142:143], v[30:31] op_sel_hi:[0,1]
	v_pk_mul_f32 v[44:45], v[142:143], v[28:29] op_sel_hi:[0,1]
	v_mfma_f32_32x32x16_bf16 v[80:95], v[148:151], v[112:115], v[80:95]
	v_mfma_f32_32x32x16_bf16 v[80:95], v[154:157], v[116:119], v[80:95]
	v_mfma_f32_32x32x16_bf16 v[80:95], v[158:161], v[120:123], v[80:95]
	s_waitcnt vmcnt(0)
	v_mfma_f32_32x32x16_bf16 v[80:95], v[162:165], v[124:127], v[80:95]
	s_nop 11
	v_pk_mul_f32 v[18:19], v[142:143], v[82:83] op_sel_hi:[0,1]
	v_pk_mul_f32 v[16:17], v[142:143], v[80:81] op_sel_hi:[0,1]
	v_lshl_add_u64 v[80:81], s[0:1], 0, v[132:133]
	v_lshrrev_b32_e32 v82, 1, v146
	s_add_i32 s0, s71, s24
	v_lshlrev_b64 v[80:81], 10, v[80:81]
	v_and_b32_e32 v82, 16, v82
	s_ashr_i32 s1, s0, 31
	v_or3_b32 v80, v80, s25, v82
	s_lshl_b64 s[0:1], s[0:1], 14
	v_lshl_add_u64 v[146:147], v[80:81], 0, s[12:13]
	v_lshl_or_b32 v80, v132, 7, s0
	s_or_b32 s0, s20, s26
	s_add_u32 s0, s0, 0xc90040
	v_mov_b32_e32 v149, s1
	s_addc_u32 s1, s21, 0
	v_pk_mul_f32 v[30:31], v[142:143], v[94:95] op_sel_hi:[0,1]
	v_pk_mul_f32 v[28:29], v[142:143], v[92:93] op_sel_hi:[0,1]
	v_pk_mul_f32 v[26:27], v[142:143], v[90:91] op_sel_hi:[0,1]
	v_pk_mul_f32 v[24:25], v[142:143], v[88:89] op_sel_hi:[0,1]
	v_pk_mul_f32 v[22:23], v[142:143], v[86:87] op_sel_hi:[0,1]
	v_pk_mul_f32 v[20:21], v[142:143], v[84:85] op_sel_hi:[0,1]
	v_and_b32_e32 v84, 3, v132
	v_lshlrev_b32_e32 v84, 9, v84
	v_lshrrev_b32_e32 v85, 2, v132
	v_lshl_or_b32 v84, v85, 4, v84
	v_and_b32_e32 v85, 0xffffc000, v80
	v_or3_b32 v148, v85, v84, v153
	v_or_b32_e32 v150, s0, v82
	v_mov_b32_e32 v151, s1
	s_branch .LBB0_716
.LBB0_715:
	s_or_b64 exec, exec, s[20:21]
	v_add_u32_e32 v14, 0x1000, v148
	s_nop 0
	v_add_f32_e32 v6, v152, v6
	s_nop 0
	s_nop 0
	s_nop 0
	v_mul_f32_e32 v6, 0x3fb8aa3b, v6
	s_nop 0
	s_nop 0
	v_exp_f32_e32 v6, v6
	s_nop 0
	v_or_b32_e32 v84, 3, v9
	s_nop 0
	s_nop 0
	s_nop 0
	v_mul_f32_e32 v6, v81, v6
	s_nop 0
	s_nop 0
	v_cmp_lt_u32_e32 vcc, v9, v140
	s_waitcnt vmcnt(0)
	v_add_f32_e32 v2, v152, v2
	v_mul_f32_e32 v2, 0x3fb8aa3b, v2
	v_cndmask_b32_e32 v81, 0, v6, vcc
	v_add_f32_e32 v6, v152, v7
	v_add_f32_e32 v7, v152, v8
	v_mul_f32_e32 v6, 0x3fb8aa3b, v6
	v_mul_f32_e32 v7, 0x3fb8aa3b, v7
	v_exp_f32_e32 v6, v6
	v_exp_f32_e32 v7, v7
	v_cmp_le_u32_e32 vcc, v84, v135
	v_or_b32_e32 v8, 2, v9
	v_exp_f32_e32 v2, v2
	v_pk_mul_f32 v[6:7], v[82:83], v[6:7]
	global_load_dwordx2 v[154:155], v148, s[98:99]
	global_load_dwordx2 v[156:157], v148, s[98:99] offset:2048
	v_cndmask_b32_e32 v131, 0, v7, vcc
	v_add_f32_e32 v7, v152, v128
	v_mul_f32_e32 v7, 0x3fb8aa3b, v7
	v_exp_f32_e32 v7, v7
	v_cmp_le_u32_e32 vcc, v8, v140
	v_add_u32_e32 v8, 9, v9
	global_load_dwordx2 v[158:159], v148, s[98:99] offset:128
	global_load_dwordx2 v[160:161], v148, s[98:99] offset:2176
	v_cndmask_b32_e32 v128, 0, v6, vcc
	v_mul_f32_e32 v82, v85, v7
	v_add_f32_e32 v6, v152, v129
	v_add_f32_e32 v7, v152, v130
	v_mul_f32_e32 v6, 0x3fb8aa3b, v6
	v_mul_f32_e32 v7, 0x3fb8aa3b, v7
	v_exp_f32_e32 v6, v6
	v_exp_f32_e32 v7, v7
	v_cmp_le_u32_e32 vcc, v8, v140
	v_or_b32_e32 v8, 11, v9
	global_load_dwordx2 v[162:163], v148, s[98:99] offset:256
	global_load_dwordx2 v[164:165], v148, s[98:99] offset:2304
	v_cndmask_b32_e32 v129, 0, v82, vcc
	v_pk_mul_f32 v[6:7], v[86:87], v[6:7]
	v_cmp_le_u32_e32 vcc, v8, v135
	v_or_b32_e32 v82, 10, v9
	v_add_u32_e32 v8, 17, v9
	v_cndmask_b32_e32 v130, 0, v7, vcc
	v_add_f32_e32 v7, v152, v10
	v_mul_f32_e32 v7, 0x3fb8aa3b, v7
	v_exp_f32_e32 v7, v7
	v_cmp_le_u32_e32 vcc, v82, v140
	global_load_dwordx2 v[166:167], v148, s[98:99] offset:384
	global_load_dwordx2 v[168:169], v148, s[98:99] offset:2432
	v_cndmask_b32_e32 v153, 0, v6, vcc
	v_mul_f32_e32 v10, v89, v7
	v_add_f32_e32 v6, v152, v11
	v_add_f32_e32 v7, v152, v12
	v_mul_f32_e32 v6, 0x3fb8aa3b, v6
	v_mul_f32_e32 v7, 0x3fb8aa3b, v7
	v_exp_f32_e32 v6, v6
	v_exp_f32_e32 v7, v7
	v_cmp_le_u32_e32 vcc, v8, v140
	v_or_b32_e32 v8, 19, v9
	v_or_b32_e32 v86, 18, v9
	v_pk_mul_f32 v[6:7], v[90:91], v[6:7]
	v_mul_f32_e32 v90, v93, v2
	v_add_f32_e32 v2, v152, v3
	v_add_f32_e32 v3, v152, v4
	v_mul_f32_e32 v2, 0x3fb8aa3b, v2
	v_mul_f32_e32 v3, 0x3fb8aa3b, v3
	v_exp_f32_e32 v2, v2
	v_exp_f32_e32 v3, v3
	v_cndmask_b32_e32 v12, 0, v10, vcc
	v_cmp_le_u32_e32 vcc, v8, v135
	v_add_u32_e32 v8, 25, v9
	v_pk_mul_f32 v[2:3], v[94:95], v[2:3]
	v_cndmask_b32_e32 v7, 0, v7, vcc
	v_cmp_le_u32_e32 vcc, v86, v140
	global_load_dwordx2 v[170:171], v14, s[98:99]
	s_nop 0
	global_load_dwordx2 v[172:173], v14, s[98:99] offset:2048
	v_cndmask_b32_e32 v6, 0, v6, vcc
	v_cmp_le_u32_e32 vcc, v8, v140
	v_or_b32_e32 v8, 27, v9
	v_or_b32_e32 v9, 26, v9
	v_cndmask_b32_e32 v4, 0, v90, vcc
	v_cmp_le_u32_e32 vcc, v8, v135
	global_load_dwordx2 v[10:11], v14, s[98:99] offset:2304
	global_load_dwordx2 v[86:87], v14, s[98:99] offset:128
	global_load_dwordx2 v[88:89], v14, s[98:99] offset:2176
	global_load_dwordx2 v[90:91], v14, s[98:99] offset:384
	global_load_dwordx2 v[92:93], v14, s[98:99] offset:2432
	v_cndmask_b32_e32 v3, 0, v3, vcc
	v_cmp_le_u32_e32 vcc, v9, v140
	global_load_dwordx2 v[8:9], v14, s[98:99] offset:256
	v_cvt_pk_bf16_f32 v82, v5, v81
	v_cvt_pk_bf16_f32 v83, v128, v131
	v_cvt_pk_bf16_f32 v84, v13, v129
	v_cvt_pk_bf16_f32 v85, v153, v130
	v_add_f32_e32 v5, v145, v5
	v_add_f32_e32 v5, v81, v5
	s_waitcnt vmcnt(14)
	v_mfma_f32_32x32x16_bf16 v[64:79], v[154:157], v[82:85], v[64:79]
	v_add_f32_e32 v5, v128, v5
	v_add_f32_e32 v5, v131, v5
	v_add_f32_e32 v5, v5, v13
	v_add_f32_e32 v5, v129, v5
	v_cndmask_b32_e32 v2, 0, v2, vcc
	v_add_f32_e32 v5, v153, v5
	v_add_f32_e32 v5, v130, v5
	s_waitcnt vmcnt(12)
	v_mfma_f32_32x32x16_bf16 v[48:63], v[158:161], v[82:85], v[48:63]
	s_add_i32 s70, s70, 32
	v_lshl_add_u64 v[146:147], v[146:147], 0, s[10:11]
	v_add_u32_e32 v148, 0x2000, v148
	s_cmp_lg_u32 s35, s70
	v_lshl_add_u64 v[150:151], v[150:151], 0, s[14:15]
	s_waitcnt vmcnt(10)
	v_mfma_f32_32x32x16_bf16 v[32:47], v[162:165], v[82:85], v[32:47]
	s_waitcnt vmcnt(8)
	v_mfma_f32_32x32x16_bf16 v[16:31], v[166:169], v[82:85], v[16:31]
	v_cvt_pk_bf16_f32 v82, v1, v12
	v_cvt_pk_bf16_f32 v83, v6, v7
	v_cvt_pk_bf16_f32 v84, v80, v4
	v_cvt_pk_bf16_f32 v85, v2, v3
	v_add_f32_e32 v1, v5, v1
	v_add_f32_e32 v1, v12, v1
	v_add_f32_e32 v1, v6, v1
	s_waitcnt vmcnt(6)
	v_mfma_f32_32x32x16_bf16 v[64:79], v[170:173], v[82:85], v[64:79]
	v_add_f32_e32 v1, v7, v1
	v_add_f32_e32 v1, v1, v80
	v_add_f32_e32 v1, v4, v1
	v_add_f32_e32 v1, v2, v1
	v_add_f32_e32 v145, v3, v1
	s_waitcnt vmcnt(3)
	v_mfma_f32_32x32x16_bf16 v[48:63], v[86:89], v[82:85], v[48:63]
	s_waitcnt vmcnt(0)
	v_mfma_f32_32x32x16_bf16 v[32:47], v[8:11], v[82:85], v[32:47]
	v_mfma_f32_32x32x16_bf16 v[16:31], v[90:93], v[82:85], v[16:31]
	s_cbranch_scc0 .LBB0_697
